# FFN-up fused epilogue regenerated: depthwise conv taps as v_fmac_f32 DPP row shifts (same fma order), 23 pct fewer VALU ops
# speedup vs baseline: 1.0056x; 1.0056x over previous
; #define PG8_STAGE(bufoff, gbase, voff) do { _Pragma("unroll") for (int _i = 0; _i < 2; ++_i) \
;         __builtin_amdgcn_global_load_lds((const unsigned*)((const char*)(gbase) + (voff)[_i]), (LAS unsigned*)(lds + (bufoff) + ldsw + _i * 8192), 16, 0, 0); } while (0)
; #define PG8_LDA(dst, b, h) do { _Pragma("unroll") for (int m = 0; m < 4; ++m) _Pragma("unroll") for (int k = 0; k < 2; ++k) dst[m][k] = *(const LAS bf16x8*)(lds + PG8_SA(b, h) + aoff + m * 2048 + k * 1024); } while (0)
; #define PG8_WAIT_V(n) asm volatile("s_waitcnt vmcnt(" #n ")" ::: "memory")
; #define PG8_BAR __builtin_amdgcn_s_barrier()
; template <class F>
; DI void gemm_phase(const int tid, LAS unsigned char* lds, const bf16_t* Ap, int lda, const bf16_t* Bp, int ldb, int M, int N, int K, int G, int c, bool direct, const F& E) {
;     ...
;         for (int t = 0; t < nt; t += 2) {
;             const bool last = (t == nt - 2);
;             const char* a1 = cA + (size_t)(t + 1) * kstep;
;             const char* a2 = last ? nA : cA + (size_t)(t + 2) * kstep; const char* b2 = last ? nB : cB + (size_t)(t + 2) * kstep;
;             const char* a3 = a2 + kstep; const char* b3 = b2 + kstep;
;             PG8_LDB(B0, 0, 0); PG8_SCHED; PG8_LDA(At, 0, 0); PG8_STAGE(PG8_SA(1, 1), a1 + hsA, voffA);
;             PG8_WAIT_L(8); PG8_BAR; PG8_WAIT_L(0); PG8_MMA(0, 0, At, B0); PG8_BAR; PG8_SCHED;
;             PG8_LDB(B1, 0, 1); PG8_STAGE(PG8_SB(0, 0), b2, voffB);
;             PG8_BAR; PG8_WAIT_L(0); PG8_MMA(0, 1, At, B1); PG8_BAR;
;             PG8_LDA(At, 0, 1); PG8_STAGE(PG8_SA(0, 0), a2, voffA);
;             PG8_BAR; PG8_WAIT_L(0); PG8_MMA(1, 0, At, B0); PG8_BAR; PG8_SCHED;
;             PG8_STAGE(PG8_SB(0, 1), b2 + hsB, voffB);
;             PG8_WAIT_V(6); PG8_BAR; PG8_MMA(1, 1, At, B1); PG8_BAR;
;             PG8_LDB(B0, 1, 0); PG8_SCHED; PG8_LDA(At, 1, 0); PG8_STAGE(PG8_SA(0, 1), a2 + hsA, voffA);
;             PG8_WAIT_L(8); PG8_BAR; PG8_WAIT_L(0); PG8_MMA(0, 0, At, B0); PG8_BAR; PG8_SCHED;
;             PG8_LDB(B1, 1, 1); PG8_STAGE(PG8_SB(1, 0), b3, voffB);
;             PG8_BAR; PG8_WAIT_L(0); PG8_MMA(0, 1, At, B1); PG8_BAR;
;             PG8_LDA(At, 1, 1); PG8_STAGE(PG8_SA(1, 0), a3, voffA);
;             PG8_BAR; PG8_WAIT_L(0); PG8_MMA(1, 0, At, B0); PG8_BAR; PG8_SCHED;
;             PG8_STAGE(PG8_SB(1, 1), b3 + hsB, voffB);
;             PG8_WAIT_V(6); PG8_BAR; PG8_MMA(1, 1, At, B1); PG8_BAR;
.LBB0_657:
	s_add_i32 s81, s76, 2
	s_add_u32 s78, s74, 0x80
	s_addc_u32 s77, s75, 0
	s_add_i32 s82, 0, 0x10000
	v_add_u32_e32 v140, s82, v189
	ds_read_b128 v[128:131], v140
	ds_read_b128 v[132:135], v140 offset:1024
	ds_read_b128 v[136:139], v140 offset:2048
	ds_read_b128 v[140:143], v140 offset:3072
	s_cmp_eq_u32 s67, s76
	s_cselect_b32 s76, s0, s78
	s_cselect_b32 s77, s1, s77
	s_cselect_b32 s79, s5, s80
	s_cselect_b32 s78, s4, s71
	v_lshl_add_u64 v[208:209], s[74:75], 0, v[204:205]
	s_add_i32 m0, s28, 0xc000
	ds_read_b128 v[144:147], v197
	ds_read_b128 v[148:151], v197 offset:1024
	ds_read_b128 v[152:155], v197 offset:2048
	ds_read_b128 v[156:159], v197 offset:3072
	ds_read_b128 v[160:163], v197 offset:4096
	ds_read_b128 v[164:167], v197 offset:5120
	ds_read_b128 v[168:171], v197 offset:6144
	ds_read_b128 v[172:175], v197 offset:7168
	global_load_lds_dwordx4 v[208:209], off
	v_lshl_add_u64 v[208:209], s[74:75], 0, v[206:207]
	s_add_i32 m0, s28, 0xe000
	s_nop 0
	global_load_lds_dwordx4 v[208:209], off
	s_waitcnt lgkmcnt(8)
	s_barrier
	s_waitcnt lgkmcnt(0)
	s_setprio 1
	s_waitcnt lgkmcnt(0)
	v_mfma_f32_16x16x32_bf16 v[124:127], v[128:131], v[144:147], v[124:127]
	v_mfma_f32_16x16x32_bf16 v[120:123], v[136:139], v[144:147], v[120:123]
	v_mfma_f32_16x16x32_bf16 v[116:119], v[128:131], v[152:155], v[116:119]
	v_mfma_f32_16x16x32_bf16 v[104:107], v[136:139], v[152:155], v[104:107]
	v_mfma_f32_16x16x32_bf16 v[100:103], v[128:131], v[160:163], v[100:103]
	v_mfma_f32_16x16x32_bf16 v[88:91], v[136:139], v[160:163], v[88:91]
	v_mfma_f32_16x16x32_bf16 v[84:87], v[128:131], v[168:171], v[84:87]
	v_mfma_f32_16x16x32_bf16 v[72:75], v[136:139], v[168:171], v[72:75]
	v_mfma_f32_16x16x32_bf16 v[124:127], v[132:135], v[148:151], v[124:127]
	v_mfma_f32_16x16x32_bf16 v[120:123], v[140:143], v[148:151], v[120:123]
	v_mfma_f32_16x16x32_bf16 v[116:119], v[132:135], v[156:159], v[116:119]
	v_mfma_f32_16x16x32_bf16 v[104:107], v[140:143], v[156:159], v[104:107]
	v_mfma_f32_16x16x32_bf16 v[100:103], v[132:135], v[164:167], v[100:103]
	v_mfma_f32_16x16x32_bf16 v[88:91], v[140:143], v[164:167], v[88:91]
	v_mfma_f32_16x16x32_bf16 v[84:87], v[132:135], v[172:175], v[84:87]
	v_mfma_f32_16x16x32_bf16 v[72:75], v[140:143], v[172:175], v[72:75]
	s_setprio 0
	s_barrier
	s_add_i32 s82, s82, s27
	v_add_u32_e32 v180, s95, v189
	v_lshl_add_u64 v[224:225], s[78:79], 0, v[178:179]
	s_mov_b32 m0, s82
	ds_read_b128 v[208:211], v180
	ds_read_b128 v[212:215], v180 offset:1024
	ds_read_b128 v[216:219], v180 offset:2048
	ds_read_b128 v[220:223], v180 offset:3072
	global_load_lds_dwordx4 v[224:225], off
	v_lshl_add_u64 v[226:227], s[78:79], 0, v[186:187]
	s_add_i32 m0, s82, 0x2000
	s_nop 0
	global_load_lds_dwordx4 v[226:227], off
	s_barrier
	s_waitcnt lgkmcnt(0)
	s_setprio 1
	s_waitcnt lgkmcnt(0)
	v_mfma_f32_16x16x32_bf16 v[112:115], v[208:211], v[144:147], v[112:115]
	v_mfma_f32_16x16x32_bf16 v[108:111], v[216:219], v[144:147], v[108:111]
	v_mfma_f32_16x16x32_bf16 v[96:99], v[208:211], v[152:155], v[96:99]
	v_mfma_f32_16x16x32_bf16 v[92:95], v[216:219], v[152:155], v[92:95]
	v_mfma_f32_16x16x32_bf16 v[80:83], v[208:211], v[160:163], v[80:83]
	v_mfma_f32_16x16x32_bf16 v[76:79], v[216:219], v[160:163], v[76:79]
	v_mfma_f32_16x16x32_bf16 v[68:71], v[208:211], v[168:171], v[68:71]
	v_mfma_f32_16x16x32_bf16 v[64:67], v[216:219], v[168:171], v[64:67]
	v_mfma_f32_16x16x32_bf16 v[112:115], v[212:215], v[148:151], v[112:115]
	v_mfma_f32_16x16x32_bf16 v[108:111], v[220:223], v[148:151], v[108:111]
	v_mfma_f32_16x16x32_bf16 v[96:99], v[212:215], v[156:159], v[96:99]
	v_mfma_f32_16x16x32_bf16 v[92:95], v[220:223], v[156:159], v[92:95]
	v_mfma_f32_16x16x32_bf16 v[80:83], v[212:215], v[164:167], v[80:83]
	v_mfma_f32_16x16x32_bf16 v[76:79], v[220:223], v[164:167], v[76:79]
	v_mfma_f32_16x16x32_bf16 v[68:71], v[212:215], v[172:175], v[68:71]
	v_mfma_f32_16x16x32_bf16 v[64:67], v[220:223], v[172:175], v[64:67]
	s_setprio 0
	s_mov_b32 m0, s28
	v_lshl_add_u64 v[228:229], s[76:77], 0, v[176:177]
	s_barrier
	ds_read_b128 v[144:147], v197 offset:16384
	ds_read_b128 v[148:151], v197 offset:17408
	ds_read_b128 v[152:155], v197 offset:18432
	ds_read_b128 v[156:159], v197 offset:19456
	ds_read_b128 v[160:163], v197 offset:20480
	ds_read_b128 v[164:167], v197 offset:21504
	ds_read_b128 v[168:171], v197 offset:22528
	ds_read_b128 v[172:175], v197 offset:23552
	global_load_lds_dwordx4 v[228:229], off
	v_lshl_add_u64 v[242:243], s[76:77], 0, v[184:185]
	s_mov_b32 m0, s34
	s_nop 0
	global_load_lds_dwordx4 v[242:243], off
	s_barrier
	s_waitcnt lgkmcnt(0)
	s_setprio 1
	s_waitcnt lgkmcnt(0)
	v_mfma_f32_16x16x32_bf16 v[60:63], v[128:131], v[144:147], v[60:63]
	v_mfma_f32_16x16x32_bf16 v[56:59], v[136:139], v[144:147], v[56:59]
	v_mfma_f32_16x16x32_bf16 v[52:55], v[128:131], v[152:155], v[52:55]
	v_mfma_f32_16x16x32_bf16 v[40:43], v[136:139], v[152:155], v[40:43]
	v_mfma_f32_16x16x32_bf16 v[36:39], v[128:131], v[160:163], v[36:39]
	v_mfma_f32_16x16x32_bf16 v[16:19], v[136:139], v[160:163], v[16:19]
	v_mfma_f32_16x16x32_bf16 v[12:15], v[128:131], v[168:171], v[12:15]
	v_mfma_f32_16x16x32_bf16 v[0:3], v[136:139], v[168:171], v[0:3]
	v_mfma_f32_16x16x32_bf16 v[60:63], v[132:135], v[148:151], v[60:63]
	v_mfma_f32_16x16x32_bf16 v[56:59], v[140:143], v[148:151], v[56:59]
	v_mfma_f32_16x16x32_bf16 v[52:55], v[132:135], v[156:159], v[52:55]
	v_mfma_f32_16x16x32_bf16 v[40:43], v[140:143], v[156:159], v[40:43]
	v_mfma_f32_16x16x32_bf16 v[36:39], v[132:135], v[164:167], v[36:39]
	v_mfma_f32_16x16x32_bf16 v[16:19], v[140:143], v[164:167], v[16:19]
	v_mfma_f32_16x16x32_bf16 v[12:15], v[132:135], v[172:175], v[12:15]
	v_mfma_f32_16x16x32_bf16 v[0:3], v[140:143], v[172:175], v[0:3]
	s_setprio 0
	s_barrier
; #define PG8_STAGE(bufoff, gbase, voff) do { _Pragma("unroll") for (int _i = 0; _i < 2; ++_i) \
;         __builtin_amdgcn_global_load_lds((const unsigned*)((const char*)(gbase) + (voff)[_i]), (LAS unsigned*)(lds + (bufoff) + ldsw + _i * 8192), 16, 0, 0); } while (0)
; #define PG8_LDA(dst, b, h) do { _Pragma("unroll") for (int m = 0; m < 4; ++m) _Pragma("unroll") for (int k = 0; k < 2; ++k) dst[m][k] = *(const LAS bf16x8*)(lds + PG8_SA(b, h) + aoff + m * 2048 + k * 1024); } while (0)
; #define PG8_LDB(dst, b, h) do { _Pragma("unroll") for (int n = 0; n < 2; ++n) _Pragma("unroll") for (int k = 0; k < 2; ++k) dst[n][k] = *(const LAS bf16x8*)(lds + PG8_SB(b, h) + boff + n * 2048 + k * 1024); } while (0)
; #define PG8_MMA(ai, bj, At, Bt) do { __builtin_amdgcn_s_setprio(1); _Pragma("unroll") for (int m = 0; m < 4; ++m) _Pragma("unroll") for (int n = 0; n < 2; ++n) _Pragma("unroll") for (int k = 0; k < 2; ++k) \
;         acc[ai][bj][m][n] = __builtin_amdgcn_mfma_f32_16x16x32_bf16(Bt[n][k], At[m][k], acc[ai][bj][m][n], 0, 0, 0); __builtin_amdgcn_s_setprio(0); } while (0)
; #define PG8_WAIT_V(n) asm volatile("s_waitcnt vmcnt(" #n ")" ::: "memory")
; #define PG8_WAIT_L(n) asm volatile("s_waitcnt lgkmcnt(" #n ")" ::: "memory")
; #define PG8_BAR __builtin_amdgcn_s_barrier()
; #define PG8_SCHED __builtin_amdgcn_sched_barrier(0)
; template <class F>
; DI void gemm_phase(const int tid, LAS unsigned char* lds, const bf16_t* Ap, int lda, const bf16_t* Bp, int ldb, int M, int N, int K, int G, int c, bool direct, const F& E) {
;     ...
;             PG8_BAR; PG8_WAIT_L(0); PG8_MMA(1, 0, At, B0); PG8_BAR; PG8_SCHED;
;             PG8_STAGE(PG8_SB(0, 1), b2 + hsB, voffB);
;             PG8_WAIT_V(6); PG8_BAR; PG8_MMA(1, 1, At, B1); PG8_BAR;
;             PG8_LDB(B0, 1, 0); PG8_SCHED; PG8_LDA(At, 1, 0); PG8_STAGE(PG8_SA(0, 1), a2 + hsA, voffA);
;             PG8_WAIT_L(8); PG8_BAR; PG8_WAIT_L(0); PG8_MMA(0, 0, At, B0); PG8_BAR; PG8_SCHED;
;             PG8_LDB(B1, 1, 1); PG8_STAGE(PG8_SB(1, 0), b3, voffB);
;             PG8_BAR; PG8_WAIT_L(0); PG8_MMA(0, 1, At, B1); PG8_BAR;
;             PG8_LDA(At, 1, 1); PG8_STAGE(PG8_SA(1, 0), a3, voffA);
;             PG8_BAR; PG8_WAIT_L(0); PG8_MMA(1, 0, At, B0); PG8_BAR; PG8_SCHED;
	s_add_u32 s78, s78, s46
	s_addc_u32 s79, s79, 0
	s_add_i32 s82, s95, s27
	v_lshl_add_u64 v[244:245], s[78:79], 0, v[178:179]
	s_mov_b32 m0, s82
	v_lshl_add_u64 v[246:247], s[78:79], 0, v[186:187]
	global_load_lds_dwordx4 v[244:245], off
	s_add_i32 m0, s82, 0x2000
	s_nop 0
	global_load_lds_dwordx4 v[246:247], off
	s_waitcnt vmcnt(6)
	s_barrier
	s_setprio 1
	v_mfma_f32_16x16x32_bf16 v[48:51], v[208:211], v[144:147], v[48:51]
	v_mfma_f32_16x16x32_bf16 v[44:47], v[216:219], v[144:147], v[44:47]
	v_mfma_f32_16x16x32_bf16 v[24:27], v[208:211], v[152:155], v[24:27]
	v_mfma_f32_16x16x32_bf16 v[20:23], v[216:219], v[152:155], v[20:23]
	v_mfma_f32_16x16x32_bf16 v[28:31], v[208:211], v[160:163], v[28:31]
	v_mfma_f32_16x16x32_bf16 v[32:35], v[216:219], v[160:163], v[32:35]
	v_mfma_f32_16x16x32_bf16 v[8:11], v[208:211], v[168:171], v[8:11]
	v_mfma_f32_16x16x32_bf16 v[4:7], v[216:219], v[168:171], v[4:7]
	v_mfma_f32_16x16x32_bf16 v[48:51], v[212:215], v[148:151], v[48:51]
	v_mfma_f32_16x16x32_bf16 v[44:47], v[220:223], v[148:151], v[44:47]
	v_mfma_f32_16x16x32_bf16 v[24:27], v[212:215], v[156:159], v[24:27]
	v_mfma_f32_16x16x32_bf16 v[20:23], v[220:223], v[156:159], v[20:23]
	v_mfma_f32_16x16x32_bf16 v[28:31], v[212:215], v[164:167], v[28:31]
	v_mfma_f32_16x16x32_bf16 v[32:35], v[220:223], v[164:167], v[32:35]
	v_mfma_f32_16x16x32_bf16 v[8:11], v[212:215], v[172:175], v[8:11]
	v_mfma_f32_16x16x32_bf16 v[4:7], v[220:223], v[172:175], v[4:7]
	s_setprio 0
	s_add_i32 s78, 0, 0x18000
	v_add_u32_e32 v140, s78, v189
	s_barrier
	ds_read_b128 v[128:131], v140
	ds_read_b128 v[132:135], v140 offset:1024
	ds_read_b128 v[136:139], v140 offset:2048
	ds_read_b128 v[140:143], v140 offset:3072
	s_add_u32 s76, s76, s24
	s_addc_u32 s77, s77, 0
	s_mov_b32 m0, s60
	v_lshl_add_u64 v[208:209], s[76:77], 0, v[176:177]
	ds_read_b128 v[144:147], v197 offset:32768
	ds_read_b128 v[148:151], v197 offset:33792
	ds_read_b128 v[152:155], v197 offset:34816
	ds_read_b128 v[156:159], v197 offset:35840
	ds_read_b128 v[160:163], v197 offset:36864
	ds_read_b128 v[164:167], v197 offset:37888
	ds_read_b128 v[168:171], v197 offset:38912
	ds_read_b128 v[172:175], v197 offset:39936
	global_load_lds_dwordx4 v[208:209], off
	v_lshl_add_u64 v[208:209], s[76:77], 0, v[184:185]
	s_mov_b32 m0, s61
	s_nop 0
	global_load_lds_dwordx4 v[208:209], off
	s_waitcnt lgkmcnt(8)
	s_barrier
	s_waitcnt lgkmcnt(0)
	s_setprio 1
	s_waitcnt lgkmcnt(0)
	v_mfma_f32_16x16x32_bf16 v[124:127], v[128:131], v[144:147], v[124:127]
	v_mfma_f32_16x16x32_bf16 v[120:123], v[136:139], v[144:147], v[120:123]
	v_mfma_f32_16x16x32_bf16 v[116:119], v[128:131], v[152:155], v[116:119]
	v_mfma_f32_16x16x32_bf16 v[104:107], v[136:139], v[152:155], v[104:107]
	v_mfma_f32_16x16x32_bf16 v[100:103], v[128:131], v[160:163], v[100:103]
	v_mfma_f32_16x16x32_bf16 v[88:91], v[136:139], v[160:163], v[88:91]
	v_mfma_f32_16x16x32_bf16 v[84:87], v[128:131], v[168:171], v[84:87]
	v_mfma_f32_16x16x32_bf16 v[72:75], v[136:139], v[168:171], v[72:75]
	v_mfma_f32_16x16x32_bf16 v[124:127], v[132:135], v[148:151], v[124:127]
	v_mfma_f32_16x16x32_bf16 v[120:123], v[140:143], v[148:151], v[120:123]
	v_mfma_f32_16x16x32_bf16 v[116:119], v[132:135], v[156:159], v[116:119]
	v_mfma_f32_16x16x32_bf16 v[104:107], v[140:143], v[156:159], v[104:107]
	v_mfma_f32_16x16x32_bf16 v[100:103], v[132:135], v[164:167], v[100:103]
	v_mfma_f32_16x16x32_bf16 v[88:91], v[140:143], v[164:167], v[88:91]
	v_mfma_f32_16x16x32_bf16 v[84:87], v[132:135], v[172:175], v[84:87]
	v_mfma_f32_16x16x32_bf16 v[72:75], v[140:143], v[172:175], v[72:75]
	s_setprio 0
	s_barrier
	s_add_i32 s76, 0, 0x1c000
	s_add_i32 s77, s78, s27
	v_add_u32_e32 v180, s76, v189
	v_lshl_add_u64 v[224:225], v[224:225], 0, s[30:31]
	s_mov_b32 m0, s77
	ds_read_b128 v[208:211], v180
	ds_read_b128 v[212:215], v180 offset:1024
	ds_read_b128 v[216:219], v180 offset:2048
	ds_read_b128 v[220:223], v180 offset:3072
	global_load_lds_dwordx4 v[224:225], off
	v_lshl_add_u64 v[224:225], v[226:227], 0, s[30:31]
	s_add_i32 m0, s77, 0x2000
	s_nop 0
	global_load_lds_dwordx4 v[224:225], off
	s_barrier
	s_waitcnt lgkmcnt(0)
	s_setprio 1
	s_waitcnt lgkmcnt(0)
	v_mfma_f32_16x16x32_bf16 v[112:115], v[208:211], v[144:147], v[112:115]
	v_mfma_f32_16x16x32_bf16 v[108:111], v[216:219], v[144:147], v[108:111]
	v_mfma_f32_16x16x32_bf16 v[96:99], v[208:211], v[152:155], v[96:99]
	v_mfma_f32_16x16x32_bf16 v[92:95], v[216:219], v[152:155], v[92:95]
	v_mfma_f32_16x16x32_bf16 v[80:83], v[208:211], v[160:163], v[80:83]
	v_mfma_f32_16x16x32_bf16 v[76:79], v[216:219], v[160:163], v[76:79]
	v_mfma_f32_16x16x32_bf16 v[68:71], v[208:211], v[168:171], v[68:71]
	v_mfma_f32_16x16x32_bf16 v[64:67], v[216:219], v[168:171], v[64:67]
	v_mfma_f32_16x16x32_bf16 v[112:115], v[212:215], v[148:151], v[112:115]
	v_mfma_f32_16x16x32_bf16 v[108:111], v[220:223], v[148:151], v[108:111]
	v_mfma_f32_16x16x32_bf16 v[96:99], v[212:215], v[156:159], v[96:99]
	v_mfma_f32_16x16x32_bf16 v[92:95], v[220:223], v[156:159], v[92:95]
	v_mfma_f32_16x16x32_bf16 v[80:83], v[212:215], v[164:167], v[80:83]
	v_mfma_f32_16x16x32_bf16 v[76:79], v[220:223], v[164:167], v[76:79]
	v_mfma_f32_16x16x32_bf16 v[68:71], v[212:215], v[172:175], v[68:71]
	v_mfma_f32_16x16x32_bf16 v[64:67], v[220:223], v[172:175], v[64:67]
	s_setprio 0
	s_mov_b32 m0, s62
	v_lshl_add_u64 v[224:225], v[228:229], 0, s[30:31]
	s_barrier
	ds_read_b128 v[144:147], v197 offset:49152
	ds_read_b128 v[148:151], v197 offset:50176
	ds_read_b128 v[152:155], v197 offset:51200
	ds_read_b128 v[156:159], v197 offset:52224
	ds_read_b128 v[160:163], v197 offset:53248
	ds_read_b128 v[164:167], v197 offset:54272
	ds_read_b128 v[168:171], v197 offset:55296
	ds_read_b128 v[172:175], v197 offset:56320
	global_load_lds_dwordx4 v[224:225], off
	v_lshl_add_u64 v[224:225], v[242:243], 0, s[30:31]
	s_mov_b32 m0, s63
	s_nop 0
	global_load_lds_dwordx4 v[224:225], off
	s_barrier
; #define PG8_STAGE(bufoff, gbase, voff) do { _Pragma("unroll") for (int _i = 0; _i < 2; ++_i) \
;         __builtin_amdgcn_global_load_lds((const unsigned*)((const char*)(gbase) + (voff)[_i]), (LAS unsigned*)(lds + (bufoff) + ldsw + _i * 8192), 16, 0, 0); } while (0)
; #define PG8_LDA(dst, b, h) do { _Pragma("unroll") for (int m = 0; m < 4; ++m) _Pragma("unroll") for (int k = 0; k < 2; ++k) dst[m][k] = *(const LAS bf16x8*)(lds + PG8_SA(b, h) + aoff + m * 2048 + k * 1024); } while (0)
; #define PG8_LDB(dst, b, h) do { _Pragma("unroll") for (int n = 0; n < 2; ++n) _Pragma("unroll") for (int k = 0; k < 2; ++k) dst[n][k] = *(const LAS bf16x8*)(lds + PG8_SB(b, h) + boff + n * 2048 + k * 1024); } while (0)
; #define PG8_WAIT_V(n) asm volatile("s_waitcnt vmcnt(" #n ")" ::: "memory")
; template <class F>
; DI void gemm_phase(const int tid, LAS unsigned char* lds, const bf16_t* Ap, int lda, const bf16_t* Bp, int ldb, int M, int N, int K, int G, int c, bool direct, const F& E) {
;     ...
;             PG8_WAIT_V(6); PG8_BAR; PG8_MMA(1, 1, At, B1); PG8_BAR;
;             PG8_LDB(B0, 1, 0); PG8_SCHED; PG8_LDA(At, 1, 0); PG8_STAGE(PG8_SA(0, 1), a2 + hsA, voffA);
;             PG8_WAIT_L(8); PG8_BAR; PG8_WAIT_L(0); PG8_MMA(0, 0, At, B0); PG8_BAR; PG8_SCHED;
;             PG8_LDB(B1, 1, 1); PG8_STAGE(PG8_SB(1, 0), b3, voffB);
;             PG8_BAR; PG8_WAIT_L(0); PG8_MMA(0, 1, At, B1); PG8_BAR;
;             PG8_LDA(At, 1, 1); PG8_STAGE(PG8_SA(1, 0), a3, voffA);
;             PG8_BAR; PG8_WAIT_L(0); PG8_MMA(1, 0, At, B0); PG8_BAR; PG8_SCHED;
;             PG8_STAGE(PG8_SB(1, 1), b3 + hsB, voffB);
;             PG8_WAIT_V(6); PG8_BAR; PG8_MMA(1, 1, At, B1); PG8_BAR;
;         }
;         if (E.kind == 7  ) E.fused(acc, cur.pm, cur.pn, wr, wc, fr, fq);
; DI void Epi::fused(const f32x4 (&acc)[2][2][4][2], int pm, int pn, int wr, int wc, int fr, int fq) const {
;     ...
;         const int ncol = pn * 256 + bj * 128 + wc * 32 + 8 * fq, j0 = (ncol >> 3) * 4;
;         const f32x4 wa0 = *(const f32x4*)(E.cf0 + j0), wa1 = *(const f32x4*)(E.cf0 + FF2 + j0), wa2 = *(const f32x4*)(E.cf0 + 2 * FF2 + j0);
;         const f32x4 wb0 = *(const f32x4*)(E.cf0 + FFH + j0), wb1 = *(const f32x4*)(E.cf0 + FF2 + FFH + j0), wb2 = *(const f32x4*)(E.cf0 + 2 * FF2 + FFH + j0);
;         const f32x4 ba = *(const f32x4*)(E.cf1 + j0), bb = *(const f32x4*)(E.cf1 + FFH + j0);
	s_waitcnt lgkmcnt(0)
	s_setprio 1
	s_waitcnt lgkmcnt(0)
	v_mfma_f32_16x16x32_bf16 v[60:63], v[128:131], v[144:147], v[60:63]
	v_mfma_f32_16x16x32_bf16 v[56:59], v[136:139], v[144:147], v[56:59]
	v_mfma_f32_16x16x32_bf16 v[52:55], v[128:131], v[152:155], v[52:55]
	v_mfma_f32_16x16x32_bf16 v[40:43], v[136:139], v[152:155], v[40:43]
	v_mfma_f32_16x16x32_bf16 v[36:39], v[128:131], v[160:163], v[36:39]
	v_mfma_f32_16x16x32_bf16 v[16:19], v[136:139], v[160:163], v[16:19]
	v_mfma_f32_16x16x32_bf16 v[12:15], v[128:131], v[168:171], v[12:15]
	v_mfma_f32_16x16x32_bf16 v[0:3], v[136:139], v[168:171], v[0:3]
	v_mfma_f32_16x16x32_bf16 v[60:63], v[132:135], v[148:151], v[60:63]
	v_mfma_f32_16x16x32_bf16 v[56:59], v[140:143], v[148:151], v[56:59]
	v_mfma_f32_16x16x32_bf16 v[52:55], v[132:135], v[156:159], v[52:55]
	v_mfma_f32_16x16x32_bf16 v[40:43], v[140:143], v[156:159], v[40:43]
	v_mfma_f32_16x16x32_bf16 v[36:39], v[132:135], v[164:167], v[36:39]
	v_mfma_f32_16x16x32_bf16 v[16:19], v[140:143], v[164:167], v[16:19]
	v_mfma_f32_16x16x32_bf16 v[12:15], v[132:135], v[172:175], v[12:15]
	v_mfma_f32_16x16x32_bf16 v[0:3], v[140:143], v[172:175], v[0:3]
	s_setprio 0
	s_barrier
	s_add_i32 s76, s76, s27
	v_lshl_add_u64 v[128:129], v[244:245], 0, s[30:31]
	s_mov_b32 m0, s76
	s_nop 0
	global_load_lds_dwordx4 v[128:129], off
	v_lshl_add_u64 v[128:129], v[246:247], 0, s[30:31]
	s_add_i32 m0, s76, 0x2000
	s_nop 0
	global_load_lds_dwordx4 v[128:129], off
	s_waitcnt vmcnt(6)
	s_barrier
	s_setprio 1
	v_mfma_f32_16x16x32_bf16 v[48:51], v[208:211], v[144:147], v[48:51]
	v_mfma_f32_16x16x32_bf16 v[44:47], v[216:219], v[144:147], v[44:47]
	v_mfma_f32_16x16x32_bf16 v[24:27], v[208:211], v[152:155], v[24:27]
	v_mfma_f32_16x16x32_bf16 v[20:23], v[216:219], v[152:155], v[20:23]
	v_mfma_f32_16x16x32_bf16 v[28:31], v[208:211], v[160:163], v[28:31]
	v_mfma_f32_16x16x32_bf16 v[32:35], v[216:219], v[160:163], v[32:35]
	v_mfma_f32_16x16x32_bf16 v[8:11], v[208:211], v[168:171], v[8:11]
	v_mfma_f32_16x16x32_bf16 v[4:7], v[216:219], v[168:171], v[4:7]
	v_mfma_f32_16x16x32_bf16 v[48:51], v[212:215], v[148:151], v[48:51]
	v_mfma_f32_16x16x32_bf16 v[44:47], v[220:223], v[148:151], v[44:47]
	v_mfma_f32_16x16x32_bf16 v[24:27], v[212:215], v[156:159], v[24:27]
	v_mfma_f32_16x16x32_bf16 v[20:23], v[220:223], v[156:159], v[20:23]
	v_mfma_f32_16x16x32_bf16 v[28:31], v[212:215], v[164:167], v[28:31]
	v_mfma_f32_16x16x32_bf16 v[32:35], v[220:223], v[164:167], v[32:35]
	v_mfma_f32_16x16x32_bf16 v[8:11], v[212:215], v[172:175], v[8:11]
	v_mfma_f32_16x16x32_bf16 v[4:7], v[220:223], v[172:175], v[4:7]
	s_setprio 0
	s_add_u32 s74, s74, 0x100
	s_addc_u32 s75, s75, 0
	s_add_u32 s71, s71, 0x100
	s_addc_u32 s80, s80, 0
	s_cmp_ge_u32 s81, s26
	s_mov_b32 s76, s81
	s_barrier
	s_cbranch_scc0 .LBB0_657
	s_mov_b64 s[76:77], -1
	s_mov_b64 s[74:75], 0
	s_cmp_lt_i32 s92, 3
	s_mov_b64 s[78:79], 0
	s_cbranch_scc1 .LBB0_688
	s_cmp_gt_i32 s92, 6
	s_mov_b64 s[78:79], -1
	s_cbranch_scc0 .LBB0_685
	v_lshl_or_b32 v240, s70, 8, v194
	v_mov_b32_e32 v241, 0
	s_lshl_b32 s71, s36, 8
	v_readlane_b32 s76, v255, 16
	s_nop 3
	s_add_i32 s71, s71, s76
	v_or_b32_e32 v199, s71, v188
	v_lshlrev_b32_e32 v238, 1, v240
	v_mov_b32_e32 v239, 0
	v_lshl_add_u64 v[136:137], s[22:23], 0, v[238:239]
	global_load_dwordx4 v[136:139], v[136:137], off
	v_readlane_b32 s76, v254, 54
	v_readlane_b32 s77, v254, 55
	s_nop 1
	v_lshl_add_u64 v[140:141], s[76:77], 0, v[238:239]
	global_load_dwordx4 v[140:143], v[140:141], off
	v_readlane_b32 s76, v254, 56
	v_readlane_b32 s77, v254, 57
	s_nop 1
	v_lshl_add_u64 v[152:153], s[76:77], 0, v[238:239]
	global_load_dwordx4 v[152:155], v[152:153], off
	v_readlane_b32 s76, v255, 4
	v_readlane_b32 s77, v255, 5
	s_nop 1
	v_lshl_add_u64 v[128:129], s[76:77], 0, v[238:239]
	global_load_dwordx4 v[128:131], v[128:129], off
	v_readlane_b32 s76, v255, 6
	v_readlane_b32 s77, v255, 7
	s_nop 1
	v_lshl_add_u64 v[132:133], s[76:77], 0, v[238:239]
	global_load_dwordx4 v[132:135], v[132:133], off
	v_readlane_b32 s76, v255, 8
	v_readlane_b32 s77, v255, 9
	s_nop 1
	v_lshl_add_u64 v[144:145], s[76:77], 0, v[238:239]
	global_load_dwordx4 v[144:147], v[144:145], off
	v_readlane_b32 s76, v254, 49
	v_readlane_b32 s77, v254, 50
	s_nop 1
	v_lshl_add_u64 v[156:157], s[76:77], 0, v[238:239]
	global_load_dwordx4 v[156:159], v[156:157], off
	v_lshl_add_u64 v[148:149], s[72:73], 0, v[238:239]
	global_load_dwordx4 v[148:151], v[148:149], off
	v_mov_b32_e32 v228, v199
	v_mov_b64_e32 v[224:225], s[12:13]
	s_movk_i32 s80, 0x1600
	v_mad_i64_i32 v[224:225], s[78:79], v228, s80, v[224:225]
	v_mov_b32_e32 v228, v240
	v_mov_b32_e32 v229, 0
	v_lshl_add_u64 v[224:225], v[228:229], 0, v[224:225]
	s_waitcnt vmcnt(0)
; DI float silu_fast(float x) { return x * __builtin_amdgcn_rcpf(1.f + __expf(-x)); }
; template <int CTRL> DI float dppf(float v) { return __builtin_bit_cast(float, __builtin_amdgcn_update_dpp(0, __builtin_bit_cast(int, v), CTRL, 0xf, 0xf, true)); }
; DI void Epi::fused(const f32x4 (&acc)[2][2][4][2], int pm, int pn, int wr, int wc, int fr, int fq) const {
;     ...
;             for (int m = 0; m < 4; ++m) {
;                 const f32x4 ca = acc[ai][bj][m][0], cb = acc[ai][bj][m][1];
;                 const int row = pm * 256 + ai * 128 + wr * 64 + m * 16 + fr;
;                 float o[4];
; #pragma unroll
;                 for (int e = 0; e < 4; ++e) {
;                     const float a1 = dppf<0x111>(ca[e]) + dppf<0x10F>(pa[e]), a2 = dppf<0x112>(ca[e]) + dppf<0x10E>(pa[e]);
;                     const float b1 = dppf<0x111>(cb[e]) + dppf<0x10F>(pb[e]), b2 = dppf<0x112>(cb[e]) + dppf<0x10E>(pb[e]);
;                     const float ya = fmaf(wa0[e], a2, fmaf(wa1[e], a1, fmaf(wa2[e], ca[e], ba[e])));
;                     const float yb = fmaf(wb0[e], b2, fmaf(wb1[e], b1, fmaf(wb2[e], cb[e], bb[e])));
;                     o[e] = silu_fast(ya) * yb; }
;                 if (m > 0 || fr >= 2) { u32x2 w; w.x = pk2(o[0], o[1]); w.y = pk2(o[2], o[3]); *(u32x2*)(E.d0 + (size_t)row * FFH + j0) = w; }
;                 if ((m == 0 && fr < 2) || (m == 3 && fr >= 14)) { float* hb = E.f0 + ((size_t)(row >> 6) * 4 + (m == 0 ? fr : fr - 12)) * FF2 + ncol; *(f32x4*)hb = ca; *(f32x4*)(hb + 4) = cb; }
;                 pa = ca; pb = cb;
	v_pk_fma_f32 v[160:161], v[152:153], v[124:125], v[156:157]
	v_pk_fma_f32 v[162:163], v[154:155], v[126:127], v[158:159]
	v_pk_fma_f32 v[164:165], v[144:145], v[120:121], v[148:149]
	v_pk_fma_f32 v[166:167], v[146:147], v[122:123], v[150:151]
	v_fmac_f32_dpp v160, v124, v140 row_shr:1 row_mask:0xf bank_mask:0xf
	v_fmac_f32_dpp v161, v125, v141 row_shr:1 row_mask:0xf bank_mask:0xf
	v_fmac_f32_dpp v162, v126, v142 row_shr:1 row_mask:0xf bank_mask:0xf
	v_fmac_f32_dpp v163, v127, v143 row_shr:1 row_mask:0xf bank_mask:0xf
	v_fmac_f32_dpp v164, v120, v132 row_shr:1 row_mask:0xf bank_mask:0xf
	v_fmac_f32_dpp v165, v121, v133 row_shr:1 row_mask:0xf bank_mask:0xf
	v_fmac_f32_dpp v166, v122, v134 row_shr:1 row_mask:0xf bank_mask:0xf
	v_fmac_f32_dpp v167, v123, v135 row_shr:1 row_mask:0xf bank_mask:0xf
	v_fmac_f32_dpp v160, v124, v136 row_shr:2 row_mask:0xf bank_mask:0xf
	v_fmac_f32_dpp v161, v125, v137 row_shr:2 row_mask:0xf bank_mask:0xf
	v_fmac_f32_dpp v162, v126, v138 row_shr:2 row_mask:0xf bank_mask:0xf
	v_fmac_f32_dpp v163, v127, v139 row_shr:2 row_mask:0xf bank_mask:0xf
	v_fmac_f32_dpp v164, v120, v128 row_shr:2 row_mask:0xf bank_mask:0xf
	v_fmac_f32_dpp v165, v121, v129 row_shr:2 row_mask:0xf bank_mask:0xf
	v_fmac_f32_dpp v166, v122, v130 row_shr:2 row_mask:0xf bank_mask:0xf
	v_fmac_f32_dpp v167, v123, v131 row_shr:2 row_mask:0xf bank_mask:0xf
	v_mul_f32_e32 v168, 0xbfb8aa3b, v160
	v_mul_f32_e32 v169, 0xbfb8aa3b, v161
	v_mul_f32_e32 v170, 0xbfb8aa3b, v162
	v_mul_f32_e32 v171, 0xbfb8aa3b, v163
	v_exp_f32_e32 v168, v168
	v_exp_f32_e32 v169, v169
	v_exp_f32_e32 v170, v170
	v_exp_f32_e32 v171, v171
	v_add_f32_e32 v168, 1.0, v168
	v_add_f32_e32 v169, 1.0, v169
	v_add_f32_e32 v170, 1.0, v170
	v_add_f32_e32 v171, 1.0, v171
	v_rcp_f32_e32 v168, v168
	v_rcp_f32_e32 v169, v169
	v_rcp_f32_e32 v170, v170
	v_rcp_f32_e32 v171, v171
	v_mov_b64_e32 v[174:175], v[224:225]
	v_pk_mul_f32 v[160:161], v[160:161], v[168:169]
	v_pk_mul_f32 v[162:163], v[162:163], v[170:171]
	v_pk_mul_f32 v[160:161], v[164:165], v[160:161]
	v_pk_mul_f32 v[162:163], v[166:167], v[162:163]
	v_cvt_pk_bf16_f32 v172, v160, v161
	v_cvt_pk_bf16_f32 v173, v162, v163
	s_and_saveexec_b64 s[76:77], s[38:39]
	global_store_dwordx2 v[174:175], v[172:173], off
	s_or_b64 exec, exec, s[76:77]
	s_ashr_i32 s80, s71, 6
	s_lshl_b32 s80, s80, 2
	v_add_u32_e32 v226, s80, v188
	v_mov_b64_e32 v[174:175], s[8:9]
	s_movk_i32 s80, 0x5800
	v_mad_i64_i32 v[174:175], s[78:79], v226, s80, v[174:175]
	v_lshl_add_u64 v[174:175], v[228:229], 2, v[174:175]
	s_and_saveexec_b64 s[76:77], s[40:41]
	global_store_dwordx4 v[174:175], v[124:127], off
	global_store_dwordx4 v[174:175], v[120:123], off offset:16
	s_or_b64 exec, exec, s[76:77]
	v_pk_fma_f32 v[208:209], v[152:153], v[116:117], v[156:157]
	v_pk_fma_f32 v[210:211], v[154:155], v[118:119], v[158:159]
	v_pk_fma_f32 v[212:213], v[144:145], v[104:105], v[148:149]
	v_pk_fma_f32 v[214:215], v[146:147], v[106:107], v[150:151]
	v_fmac_f32_dpp v208, v116, v140 row_shr:1 row_mask:0xf bank_mask:0xf
	v_fmac_f32_dpp v209, v117, v141 row_shr:1 row_mask:0xf bank_mask:0xf
	v_fmac_f32_dpp v210, v118, v142 row_shr:1 row_mask:0xf bank_mask:0xf
	v_fmac_f32_dpp v211, v119, v143 row_shr:1 row_mask:0xf bank_mask:0xf
	v_fmac_f32_dpp v212, v104, v132 row_shr:1 row_mask:0xf bank_mask:0xf
	v_fmac_f32_dpp v213, v105, v133 row_shr:1 row_mask:0xf bank_mask:0xf
	v_fmac_f32_dpp v214, v106, v134 row_shr:1 row_mask:0xf bank_mask:0xf
	v_fmac_f32_dpp v215, v107, v135 row_shr:1 row_mask:0xf bank_mask:0xf
	v_fmac_f32_dpp v208, v124, v140 row_shl:15 row_mask:0xf bank_mask:0xf
	v_fmac_f32_dpp v209, v125, v141 row_shl:15 row_mask:0xf bank_mask:0xf
	v_fmac_f32_dpp v210, v126, v142 row_shl:15 row_mask:0xf bank_mask:0xf
	v_fmac_f32_dpp v211, v127, v143 row_shl:15 row_mask:0xf bank_mask:0xf
	v_fmac_f32_dpp v212, v120, v132 row_shl:15 row_mask:0xf bank_mask:0xf
	v_fmac_f32_dpp v213, v121, v133 row_shl:15 row_mask:0xf bank_mask:0xf
	v_fmac_f32_dpp v214, v122, v134 row_shl:15 row_mask:0xf bank_mask:0xf
	v_fmac_f32_dpp v215, v123, v135 row_shl:15 row_mask:0xf bank_mask:0xf
	v_fmac_f32_dpp v208, v116, v136 row_shr:2 row_mask:0xf bank_mask:0xf
	v_fmac_f32_dpp v209, v117, v137 row_shr:2 row_mask:0xf bank_mask:0xf
	v_fmac_f32_dpp v210, v118, v138 row_shr:2 row_mask:0xf bank_mask:0xf
	v_fmac_f32_dpp v211, v119, v139 row_shr:2 row_mask:0xf bank_mask:0xf
	v_fmac_f32_dpp v212, v104, v128 row_shr:2 row_mask:0xf bank_mask:0xf
	v_fmac_f32_dpp v213, v105, v129 row_shr:2 row_mask:0xf bank_mask:0xf
	v_fmac_f32_dpp v214, v106, v130 row_shr:2 row_mask:0xf bank_mask:0xf
	v_fmac_f32_dpp v215, v107, v131 row_shr:2 row_mask:0xf bank_mask:0xf
	v_fmac_f32_dpp v208, v124, v136 row_shl:14 row_mask:0xf bank_mask:0xf
	v_fmac_f32_dpp v209, v125, v137 row_shl:14 row_mask:0xf bank_mask:0xf
	v_fmac_f32_dpp v210, v126, v138 row_shl:14 row_mask:0xf bank_mask:0xf
	v_fmac_f32_dpp v211, v127, v139 row_shl:14 row_mask:0xf bank_mask:0xf
	v_fmac_f32_dpp v212, v120, v128 row_shl:14 row_mask:0xf bank_mask:0xf
	v_fmac_f32_dpp v213, v121, v129 row_shl:14 row_mask:0xf bank_mask:0xf
	v_fmac_f32_dpp v214, v122, v130 row_shl:14 row_mask:0xf bank_mask:0xf
	v_fmac_f32_dpp v215, v123, v131 row_shl:14 row_mask:0xf bank_mask:0xf
	v_mul_f32_e32 v216, 0xbfb8aa3b, v208
	v_mul_f32_e32 v217, 0xbfb8aa3b, v209
	v_mul_f32_e32 v218, 0xbfb8aa3b, v210
	v_mul_f32_e32 v219, 0xbfb8aa3b, v211
	v_exp_f32_e32 v216, v216
	v_exp_f32_e32 v217, v217
	v_exp_f32_e32 v218, v218
	v_exp_f32_e32 v219, v219
	v_add_f32_e32 v216, 1.0, v216
	v_add_f32_e32 v217, 1.0, v217
	v_add_f32_e32 v218, 1.0, v218
	v_add_f32_e32 v219, 1.0, v219
	v_rcp_f32_e32 v216, v216
	v_rcp_f32_e32 v217, v217
; DI float silu_fast(float x) { return x * __builtin_amdgcn_rcpf(1.f + __expf(-x)); }
; template <int CTRL> DI float dppf(float v) { return __builtin_bit_cast(float, __builtin_amdgcn_update_dpp(0, __builtin_bit_cast(int, v), CTRL, 0xf, 0xf, true)); }
; DI void Epi::fused(const f32x4 (&acc)[2][2][4][2], int pm, int pn, int wr, int wc, int fr, int fq) const {
;     ...
;             for (int m = 0; m < 4; ++m) {
;                 const f32x4 ca = acc[ai][bj][m][0], cb = acc[ai][bj][m][1];
;                 const int row = pm * 256 + ai * 128 + wr * 64 + m * 16 + fr;
;                 float o[4];
; #pragma unroll
;                 for (int e = 0; e < 4; ++e) {
;                     const float a1 = dppf<0x111>(ca[e]) + dppf<0x10F>(pa[e]), a2 = dppf<0x112>(ca[e]) + dppf<0x10E>(pa[e]);
;                     const float b1 = dppf<0x111>(cb[e]) + dppf<0x10F>(pb[e]), b2 = dppf<0x112>(cb[e]) + dppf<0x10E>(pb[e]);
;                     const float ya = fmaf(wa0[e], a2, fmaf(wa1[e], a1, fmaf(wa2[e], ca[e], ba[e])));
;                     const float yb = fmaf(wb0[e], b2, fmaf(wb1[e], b1, fmaf(wb2[e], cb[e], bb[e])));
;                     o[e] = silu_fast(ya) * yb; }
;                 if (m > 0 || fr >= 2) { u32x2 w; w.x = pk2(o[0], o[1]); w.y = pk2(o[2], o[3]); *(u32x2*)(E.d0 + (size_t)row * FFH + j0) = w; }
;                 if ((m == 0 && fr < 2) || (m == 3 && fr >= 14)) { float* hb = E.f0 + ((size_t)(row >> 6) * 4 + (m == 0 ? fr : fr - 12)) * FF2 + ncol; *(f32x4*)hb = ca; *(f32x4*)(hb + 4) = cb; }
;                 pa = ca; pb = cb;
	v_rcp_f32_e32 v218, v218
	v_rcp_f32_e32 v219, v219
	s_mov_b32 s80, 0x16000
	s_mov_b32 s81, 0
	v_lshl_add_u64 v[222:223], v[224:225], 0, s[80:81]
	v_pk_mul_f32 v[208:209], v[208:209], v[216:217]
	v_pk_mul_f32 v[210:211], v[210:211], v[218:219]
	v_pk_mul_f32 v[208:209], v[212:213], v[208:209]
	v_pk_mul_f32 v[210:211], v[214:215], v[210:211]
	v_cvt_pk_bf16_f32 v220, v208, v209
	v_cvt_pk_bf16_f32 v221, v210, v211
	global_store_dwordx2 v[222:223], v[220:221], off
	v_pk_fma_f32 v[160:161], v[152:153], v[100:101], v[156:157]
	v_pk_fma_f32 v[162:163], v[154:155], v[102:103], v[158:159]
	v_pk_fma_f32 v[164:165], v[144:145], v[88:89], v[148:149]
	v_pk_fma_f32 v[166:167], v[146:147], v[90:91], v[150:151]
	v_fmac_f32_dpp v160, v100, v140 row_shr:1 row_mask:0xf bank_mask:0xf
	v_fmac_f32_dpp v161, v101, v141 row_shr:1 row_mask:0xf bank_mask:0xf
	v_fmac_f32_dpp v162, v102, v142 row_shr:1 row_mask:0xf bank_mask:0xf
	v_fmac_f32_dpp v163, v103, v143 row_shr:1 row_mask:0xf bank_mask:0xf
	v_fmac_f32_dpp v164, v88, v132 row_shr:1 row_mask:0xf bank_mask:0xf
	v_fmac_f32_dpp v165, v89, v133 row_shr:1 row_mask:0xf bank_mask:0xf
	v_fmac_f32_dpp v166, v90, v134 row_shr:1 row_mask:0xf bank_mask:0xf
	v_fmac_f32_dpp v167, v91, v135 row_shr:1 row_mask:0xf bank_mask:0xf
	v_fmac_f32_dpp v160, v116, v140 row_shl:15 row_mask:0xf bank_mask:0xf
	v_fmac_f32_dpp v161, v117, v141 row_shl:15 row_mask:0xf bank_mask:0xf
	v_fmac_f32_dpp v162, v118, v142 row_shl:15 row_mask:0xf bank_mask:0xf
	v_fmac_f32_dpp v163, v119, v143 row_shl:15 row_mask:0xf bank_mask:0xf
	v_fmac_f32_dpp v164, v104, v132 row_shl:15 row_mask:0xf bank_mask:0xf
	v_fmac_f32_dpp v165, v105, v133 row_shl:15 row_mask:0xf bank_mask:0xf
	v_fmac_f32_dpp v166, v106, v134 row_shl:15 row_mask:0xf bank_mask:0xf
	v_fmac_f32_dpp v167, v107, v135 row_shl:15 row_mask:0xf bank_mask:0xf
	v_fmac_f32_dpp v160, v100, v136 row_shr:2 row_mask:0xf bank_mask:0xf
	v_fmac_f32_dpp v161, v101, v137 row_shr:2 row_mask:0xf bank_mask:0xf
	v_fmac_f32_dpp v162, v102, v138 row_shr:2 row_mask:0xf bank_mask:0xf
	v_fmac_f32_dpp v163, v103, v139 row_shr:2 row_mask:0xf bank_mask:0xf
	v_fmac_f32_dpp v164, v88, v128 row_shr:2 row_mask:0xf bank_mask:0xf
	v_fmac_f32_dpp v165, v89, v129 row_shr:2 row_mask:0xf bank_mask:0xf
	v_fmac_f32_dpp v166, v90, v130 row_shr:2 row_mask:0xf bank_mask:0xf
	v_fmac_f32_dpp v167, v91, v131 row_shr:2 row_mask:0xf bank_mask:0xf
	v_fmac_f32_dpp v160, v116, v136 row_shl:14 row_mask:0xf bank_mask:0xf
	v_fmac_f32_dpp v161, v117, v137 row_shl:14 row_mask:0xf bank_mask:0xf
	v_fmac_f32_dpp v162, v118, v138 row_shl:14 row_mask:0xf bank_mask:0xf
	v_fmac_f32_dpp v163, v119, v139 row_shl:14 row_mask:0xf bank_mask:0xf
	v_fmac_f32_dpp v164, v104, v128 row_shl:14 row_mask:0xf bank_mask:0xf
	v_fmac_f32_dpp v165, v105, v129 row_shl:14 row_mask:0xf bank_mask:0xf
	v_fmac_f32_dpp v166, v106, v130 row_shl:14 row_mask:0xf bank_mask:0xf
	v_fmac_f32_dpp v167, v107, v131 row_shl:14 row_mask:0xf bank_mask:0xf
	v_mul_f32_e32 v168, 0xbfb8aa3b, v160
	v_mul_f32_e32 v169, 0xbfb8aa3b, v161
	v_mul_f32_e32 v170, 0xbfb8aa3b, v162
	v_mul_f32_e32 v171, 0xbfb8aa3b, v163
	v_exp_f32_e32 v168, v168
	v_exp_f32_e32 v169, v169
	v_exp_f32_e32 v170, v170
	v_exp_f32_e32 v171, v171
	v_add_f32_e32 v168, 1.0, v168
	v_add_f32_e32 v169, 1.0, v169
	v_add_f32_e32 v170, 1.0, v170
	v_add_f32_e32 v171, 1.0, v171
	v_rcp_f32_e32 v168, v168
	v_rcp_f32_e32 v169, v169
	v_rcp_f32_e32 v170, v170
	v_rcp_f32_e32 v171, v171
	s_mov_b32 s80, 0x2c000
	s_mov_b32 s81, 0
	v_lshl_add_u64 v[174:175], v[224:225], 0, s[80:81]
	v_pk_mul_f32 v[160:161], v[160:161], v[168:169]
	v_pk_mul_f32 v[162:163], v[162:163], v[170:171]
	v_pk_mul_f32 v[160:161], v[164:165], v[160:161]
	v_pk_mul_f32 v[162:163], v[166:167], v[162:163]
	v_cvt_pk_bf16_f32 v172, v160, v161
	v_cvt_pk_bf16_f32 v173, v162, v163
	global_store_dwordx2 v[174:175], v[172:173], off
	v_pk_fma_f32 v[208:209], v[152:153], v[84:85], v[156:157]
	v_pk_fma_f32 v[210:211], v[154:155], v[86:87], v[158:159]
	v_pk_fma_f32 v[212:213], v[144:145], v[72:73], v[148:149]
	v_pk_fma_f32 v[214:215], v[146:147], v[74:75], v[150:151]
	v_fmac_f32_dpp v208, v84, v140 row_shr:1 row_mask:0xf bank_mask:0xf
	v_fmac_f32_dpp v209, v85, v141 row_shr:1 row_mask:0xf bank_mask:0xf
	v_fmac_f32_dpp v210, v86, v142 row_shr:1 row_mask:0xf bank_mask:0xf
	v_fmac_f32_dpp v211, v87, v143 row_shr:1 row_mask:0xf bank_mask:0xf
	v_fmac_f32_dpp v212, v72, v132 row_shr:1 row_mask:0xf bank_mask:0xf
	v_fmac_f32_dpp v213, v73, v133 row_shr:1 row_mask:0xf bank_mask:0xf
	v_fmac_f32_dpp v214, v74, v134 row_shr:1 row_mask:0xf bank_mask:0xf
	v_fmac_f32_dpp v215, v75, v135 row_shr:1 row_mask:0xf bank_mask:0xf
	v_fmac_f32_dpp v208, v100, v140 row_shl:15 row_mask:0xf bank_mask:0xf
	v_fmac_f32_dpp v209, v101, v141 row_shl:15 row_mask:0xf bank_mask:0xf
	v_fmac_f32_dpp v210, v102, v142 row_shl:15 row_mask:0xf bank_mask:0xf
	v_fmac_f32_dpp v211, v103, v143 row_shl:15 row_mask:0xf bank_mask:0xf
	v_fmac_f32_dpp v212, v88, v132 row_shl:15 row_mask:0xf bank_mask:0xf
	v_fmac_f32_dpp v213, v89, v133 row_shl:15 row_mask:0xf bank_mask:0xf
	v_fmac_f32_dpp v214, v90, v134 row_shl:15 row_mask:0xf bank_mask:0xf
	v_fmac_f32_dpp v215, v91, v135 row_shl:15 row_mask:0xf bank_mask:0xf
	v_fmac_f32_dpp v208, v84, v136 row_shr:2 row_mask:0xf bank_mask:0xf
	v_fmac_f32_dpp v209, v85, v137 row_shr:2 row_mask:0xf bank_mask:0xf
	v_fmac_f32_dpp v210, v86, v138 row_shr:2 row_mask:0xf bank_mask:0xf
	v_fmac_f32_dpp v211, v87, v139 row_shr:2 row_mask:0xf bank_mask:0xf
	v_fmac_f32_dpp v212, v72, v128 row_shr:2 row_mask:0xf bank_mask:0xf
	v_fmac_f32_dpp v213, v73, v129 row_shr:2 row_mask:0xf bank_mask:0xf
; DI float silu_fast(float x) { return x * __builtin_amdgcn_rcpf(1.f + __expf(-x)); }
; template <int CTRL> DI float dppf(float v) { return __builtin_bit_cast(float, __builtin_amdgcn_update_dpp(0, __builtin_bit_cast(int, v), CTRL, 0xf, 0xf, true)); }
; DI void Epi::fused(const f32x4 (&acc)[2][2][4][2], int pm, int pn, int wr, int wc, int fr, int fq) const {
;     ...
;         const int ncol = pn * 256 + bj * 128 + wc * 32 + 8 * fq, j0 = (ncol >> 3) * 4;
;         const f32x4 wa0 = *(const f32x4*)(E.cf0 + j0), wa1 = *(const f32x4*)(E.cf0 + FF2 + j0), wa2 = *(const f32x4*)(E.cf0 + 2 * FF2 + j0);
;         const f32x4 wb0 = *(const f32x4*)(E.cf0 + FFH + j0), wb1 = *(const f32x4*)(E.cf0 + FF2 + FFH + j0), wb2 = *(const f32x4*)(E.cf0 + 2 * FF2 + FFH + j0);
;         const f32x4 ba = *(const f32x4*)(E.cf1 + j0), bb = *(const f32x4*)(E.cf1 + FFH + j0);
;     ...
;             for (int m = 0; m < 4; ++m) {
;                 const f32x4 ca = acc[ai][bj][m][0], cb = acc[ai][bj][m][1];
;                 const int row = pm * 256 + ai * 128 + wr * 64 + m * 16 + fr;
;                 float o[4];
; #pragma unroll
;                 for (int e = 0; e < 4; ++e) {
;                     const float a1 = dppf<0x111>(ca[e]) + dppf<0x10F>(pa[e]), a2 = dppf<0x112>(ca[e]) + dppf<0x10E>(pa[e]);
;                     const float b1 = dppf<0x111>(cb[e]) + dppf<0x10F>(pb[e]), b2 = dppf<0x112>(cb[e]) + dppf<0x10E>(pb[e]);
;                     const float ya = fmaf(wa0[e], a2, fmaf(wa1[e], a1, fmaf(wa2[e], ca[e], ba[e])));
;                     const float yb = fmaf(wb0[e], b2, fmaf(wb1[e], b1, fmaf(wb2[e], cb[e], bb[e])));
;                     o[e] = silu_fast(ya) * yb; }
;                 if (m > 0 || fr >= 2) { u32x2 w; w.x = pk2(o[0], o[1]); w.y = pk2(o[2], o[3]); *(u32x2*)(E.d0 + (size_t)row * FFH + j0) = w; }
;                 if ((m == 0 && fr < 2) || (m == 3 && fr >= 14)) { float* hb = E.f0 + ((size_t)(row >> 6) * 4 + (m == 0 ? fr : fr - 12)) * FF2 + ncol; *(f32x4*)hb = ca; *(f32x4*)(hb + 4) = cb; }
;                 pa = ca; pb = cb;
	v_fmac_f32_dpp v214, v74, v130 row_shr:2 row_mask:0xf bank_mask:0xf
	v_fmac_f32_dpp v215, v75, v131 row_shr:2 row_mask:0xf bank_mask:0xf
	v_fmac_f32_dpp v208, v100, v136 row_shl:14 row_mask:0xf bank_mask:0xf
	v_fmac_f32_dpp v209, v101, v137 row_shl:14 row_mask:0xf bank_mask:0xf
	v_fmac_f32_dpp v210, v102, v138 row_shl:14 row_mask:0xf bank_mask:0xf
	v_fmac_f32_dpp v211, v103, v139 row_shl:14 row_mask:0xf bank_mask:0xf
	v_fmac_f32_dpp v212, v88, v128 row_shl:14 row_mask:0xf bank_mask:0xf
	v_fmac_f32_dpp v213, v89, v129 row_shl:14 row_mask:0xf bank_mask:0xf
	v_fmac_f32_dpp v214, v90, v130 row_shl:14 row_mask:0xf bank_mask:0xf
	v_fmac_f32_dpp v215, v91, v131 row_shl:14 row_mask:0xf bank_mask:0xf
	v_mul_f32_e32 v216, 0xbfb8aa3b, v208
	v_mul_f32_e32 v217, 0xbfb8aa3b, v209
	v_mul_f32_e32 v218, 0xbfb8aa3b, v210
	v_mul_f32_e32 v219, 0xbfb8aa3b, v211
	v_exp_f32_e32 v216, v216
	v_exp_f32_e32 v217, v217
	v_exp_f32_e32 v218, v218
	v_exp_f32_e32 v219, v219
	v_add_f32_e32 v216, 1.0, v216
	v_add_f32_e32 v217, 1.0, v217
	v_add_f32_e32 v218, 1.0, v218
	v_add_f32_e32 v219, 1.0, v219
	v_rcp_f32_e32 v216, v216
	v_rcp_f32_e32 v217, v217
	v_rcp_f32_e32 v218, v218
	v_rcp_f32_e32 v219, v219
	s_mov_b32 s80, 0x42000
	s_mov_b32 s81, 0
	v_lshl_add_u64 v[222:223], v[224:225], 0, s[80:81]
	v_pk_mul_f32 v[208:209], v[208:209], v[216:217]
	v_pk_mul_f32 v[210:211], v[210:211], v[218:219]
	v_pk_mul_f32 v[208:209], v[212:213], v[208:209]
	v_pk_mul_f32 v[210:211], v[214:215], v[210:211]
	v_cvt_pk_bf16_f32 v220, v208, v209
	v_cvt_pk_bf16_f32 v221, v210, v211
	global_store_dwordx2 v[222:223], v[220:221], off
	s_ashr_i32 s80, s71, 6
	s_lshl_b32 s80, s80, 2
	v_add_u32_e32 v226, s80, v190
	v_mov_b64_e32 v[222:223], s[8:9]
	s_movk_i32 s80, 0x5800
	v_mad_i64_i32 v[222:223], s[78:79], v226, s80, v[222:223]
	v_lshl_add_u64 v[222:223], v[228:229], 2, v[222:223]
	s_and_saveexec_b64 s[76:77], s[42:43]
	global_store_dwordx4 v[222:223], v[84:87], off
	global_store_dwordx4 v[222:223], v[72:75], off offset:16
	s_or_b64 exec, exec, s[76:77]
	v_add_u32_e32 v238, 0x80, v240
	v_lshlrev_b32_e32 v238, 1, v238
	v_mov_b32_e32 v239, 0
	v_lshl_add_u64 v[84:85], s[22:23], 0, v[238:239]
	global_load_dwordx4 v[84:87], v[84:85], off
	v_readlane_b32 s76, v254, 54
	v_readlane_b32 s77, v254, 55
	s_nop 1
	v_lshl_add_u64 v[88:89], s[76:77], 0, v[238:239]
	global_load_dwordx4 v[88:91], v[88:89], off
	v_readlane_b32 s76, v254, 56
	v_readlane_b32 s77, v254, 57
	s_nop 1
	v_lshl_add_u64 v[100:101], s[76:77], 0, v[238:239]
	global_load_dwordx4 v[100:103], v[100:101], off
	v_readlane_b32 s76, v255, 4
	v_readlane_b32 s77, v255, 5
	s_nop 1
	v_lshl_add_u64 v[104:105], s[76:77], 0, v[238:239]
	global_load_dwordx4 v[104:107], v[104:105], off
	v_readlane_b32 s76, v255, 6
	v_readlane_b32 s77, v255, 7
	s_nop 1
	v_lshl_add_u64 v[116:117], s[76:77], 0, v[238:239]
	global_load_dwordx4 v[116:119], v[116:117], off
	v_readlane_b32 s76, v255, 8
	v_readlane_b32 s77, v255, 9
	s_nop 1
	v_lshl_add_u64 v[120:121], s[76:77], 0, v[238:239]
	global_load_dwordx4 v[120:123], v[120:121], off
	v_readlane_b32 s76, v254, 49
	v_readlane_b32 s77, v254, 50
	s_nop 1
	v_lshl_add_u64 v[124:125], s[76:77], 0, v[238:239]
	global_load_dwordx4 v[124:127], v[124:125], off
	v_lshl_add_u64 v[72:73], s[72:73], 0, v[238:239]
	global_load_dwordx4 v[72:75], v[72:73], off
	v_add_u32_e32 v228, 128, v199
	v_mov_b64_e32 v[224:225], s[12:13]
	s_movk_i32 s80, 0x1600
	v_mad_i64_i32 v[224:225], s[78:79], v228, s80, v[224:225]
	v_mov_b32_e32 v228, v240
	v_mov_b32_e32 v229, 0
	v_lshl_add_u64 v[224:225], v[228:229], 0, v[224:225]
	v_pk_fma_f32 v[160:161], v[152:153], v[60:61], v[156:157]
	v_pk_fma_f32 v[162:163], v[154:155], v[62:63], v[158:159]
	v_pk_fma_f32 v[164:165], v[144:145], v[56:57], v[148:149]
	v_pk_fma_f32 v[166:167], v[146:147], v[58:59], v[150:151]
	v_fmac_f32_dpp v160, v60, v140 row_shr:1 row_mask:0xf bank_mask:0xf
	v_fmac_f32_dpp v161, v61, v141 row_shr:1 row_mask:0xf bank_mask:0xf
	v_fmac_f32_dpp v162, v62, v142 row_shr:1 row_mask:0xf bank_mask:0xf
	v_fmac_f32_dpp v163, v63, v143 row_shr:1 row_mask:0xf bank_mask:0xf
	v_fmac_f32_dpp v164, v56, v132 row_shr:1 row_mask:0xf bank_mask:0xf
	v_fmac_f32_dpp v165, v57, v133 row_shr:1 row_mask:0xf bank_mask:0xf
	v_fmac_f32_dpp v166, v58, v134 row_shr:1 row_mask:0xf bank_mask:0xf
	v_fmac_f32_dpp v167, v59, v135 row_shr:1 row_mask:0xf bank_mask:0xf
	v_fmac_f32_dpp v160, v60, v136 row_shr:2 row_mask:0xf bank_mask:0xf
	v_fmac_f32_dpp v161, v61, v137 row_shr:2 row_mask:0xf bank_mask:0xf
	v_fmac_f32_dpp v162, v62, v138 row_shr:2 row_mask:0xf bank_mask:0xf
	v_fmac_f32_dpp v163, v63, v139 row_shr:2 row_mask:0xf bank_mask:0xf
	v_fmac_f32_dpp v164, v56, v128 row_shr:2 row_mask:0xf bank_mask:0xf
	v_fmac_f32_dpp v165, v57, v129 row_shr:2 row_mask:0xf bank_mask:0xf
	v_fmac_f32_dpp v166, v58, v130 row_shr:2 row_mask:0xf bank_mask:0xf
	v_fmac_f32_dpp v167, v59, v131 row_shr:2 row_mask:0xf bank_mask:0xf
	v_mul_f32_e32 v168, 0xbfb8aa3b, v160
	v_mul_f32_e32 v169, 0xbfb8aa3b, v161
	v_mul_f32_e32 v170, 0xbfb8aa3b, v162
	v_mul_f32_e32 v171, 0xbfb8aa3b, v163
	v_exp_f32_e32 v168, v168
	v_exp_f32_e32 v169, v169
	v_exp_f32_e32 v170, v170
	v_exp_f32_e32 v171, v171
	v_add_f32_e32 v168, 1.0, v168
	v_add_f32_e32 v169, 1.0, v169
	v_add_f32_e32 v170, 1.0, v170
	v_add_f32_e32 v171, 1.0, v171
	v_rcp_f32_e32 v168, v168
	v_rcp_f32_e32 v169, v169
	v_rcp_f32_e32 v170, v170
	v_rcp_f32_e32 v171, v171
	v_mov_b64_e32 v[174:175], v[224:225]
	v_pk_mul_f32 v[160:161], v[160:161], v[168:169]
	v_pk_mul_f32 v[162:163], v[162:163], v[170:171]
	v_pk_mul_f32 v[160:161], v[164:165], v[160:161]
	v_pk_mul_f32 v[162:163], v[166:167], v[162:163]
	v_cvt_pk_bf16_f32 v172, v160, v161
; DI float silu_fast(float x) { return x * __builtin_amdgcn_rcpf(1.f + __expf(-x)); }
; template <int CTRL> DI float dppf(float v) { return __builtin_bit_cast(float, __builtin_amdgcn_update_dpp(0, __builtin_bit_cast(int, v), CTRL, 0xf, 0xf, true)); }
; DI void Epi::fused(const f32x4 (&acc)[2][2][4][2], int pm, int pn, int wr, int wc, int fr, int fq) const {
;     ...
;             for (int m = 0; m < 4; ++m) {
;                 const f32x4 ca = acc[ai][bj][m][0], cb = acc[ai][bj][m][1];
;                 const int row = pm * 256 + ai * 128 + wr * 64 + m * 16 + fr;
;                 float o[4];
; #pragma unroll
;                 for (int e = 0; e < 4; ++e) {
;                     const float a1 = dppf<0x111>(ca[e]) + dppf<0x10F>(pa[e]), a2 = dppf<0x112>(ca[e]) + dppf<0x10E>(pa[e]);
;                     const float b1 = dppf<0x111>(cb[e]) + dppf<0x10F>(pb[e]), b2 = dppf<0x112>(cb[e]) + dppf<0x10E>(pb[e]);
;                     const float ya = fmaf(wa0[e], a2, fmaf(wa1[e], a1, fmaf(wa2[e], ca[e], ba[e])));
;                     const float yb = fmaf(wb0[e], b2, fmaf(wb1[e], b1, fmaf(wb2[e], cb[e], bb[e])));
;                     o[e] = silu_fast(ya) * yb; }
;                 if (m > 0 || fr >= 2) { u32x2 w; w.x = pk2(o[0], o[1]); w.y = pk2(o[2], o[3]); *(u32x2*)(E.d0 + (size_t)row * FFH + j0) = w; }
;                 if ((m == 0 && fr < 2) || (m == 3 && fr >= 14)) { float* hb = E.f0 + ((size_t)(row >> 6) * 4 + (m == 0 ? fr : fr - 12)) * FF2 + ncol; *(f32x4*)hb = ca; *(f32x4*)(hb + 4) = cb; }
;                 pa = ca; pb = cb;
	v_cvt_pk_bf16_f32 v173, v162, v163
	s_and_saveexec_b64 s[76:77], s[38:39]
	global_store_dwordx2 v[174:175], v[172:173], off
	s_or_b64 exec, exec, s[76:77]
	s_ashr_i32 s80, s71, 6
	s_lshl_b32 s80, s80, 2
	s_add_i32 s80, s80, 8
	v_add_u32_e32 v226, s80, v188
	v_mov_b64_e32 v[174:175], s[8:9]
	s_movk_i32 s80, 0x5800
	v_mad_i64_i32 v[174:175], s[78:79], v226, s80, v[174:175]
	v_lshl_add_u64 v[174:175], v[228:229], 2, v[174:175]
	s_and_saveexec_b64 s[76:77], s[40:41]
	global_store_dwordx4 v[174:175], v[60:63], off
	global_store_dwordx4 v[174:175], v[56:59], off offset:16
	s_or_b64 exec, exec, s[76:77]
	v_pk_fma_f32 v[208:209], v[152:153], v[52:53], v[156:157]
	v_pk_fma_f32 v[210:211], v[154:155], v[54:55], v[158:159]
	v_pk_fma_f32 v[212:213], v[144:145], v[40:41], v[148:149]
	v_pk_fma_f32 v[214:215], v[146:147], v[42:43], v[150:151]
	v_fmac_f32_dpp v208, v52, v140 row_shr:1 row_mask:0xf bank_mask:0xf
	v_fmac_f32_dpp v209, v53, v141 row_shr:1 row_mask:0xf bank_mask:0xf
	v_fmac_f32_dpp v210, v54, v142 row_shr:1 row_mask:0xf bank_mask:0xf
	v_fmac_f32_dpp v211, v55, v143 row_shr:1 row_mask:0xf bank_mask:0xf
	v_fmac_f32_dpp v212, v40, v132 row_shr:1 row_mask:0xf bank_mask:0xf
	v_fmac_f32_dpp v213, v41, v133 row_shr:1 row_mask:0xf bank_mask:0xf
	v_fmac_f32_dpp v214, v42, v134 row_shr:1 row_mask:0xf bank_mask:0xf
	v_fmac_f32_dpp v215, v43, v135 row_shr:1 row_mask:0xf bank_mask:0xf
	v_fmac_f32_dpp v208, v60, v140 row_shl:15 row_mask:0xf bank_mask:0xf
	v_fmac_f32_dpp v209, v61, v141 row_shl:15 row_mask:0xf bank_mask:0xf
	v_fmac_f32_dpp v210, v62, v142 row_shl:15 row_mask:0xf bank_mask:0xf
	v_fmac_f32_dpp v211, v63, v143 row_shl:15 row_mask:0xf bank_mask:0xf
	v_fmac_f32_dpp v212, v56, v132 row_shl:15 row_mask:0xf bank_mask:0xf
	v_fmac_f32_dpp v213, v57, v133 row_shl:15 row_mask:0xf bank_mask:0xf
	v_fmac_f32_dpp v214, v58, v134 row_shl:15 row_mask:0xf bank_mask:0xf
	v_fmac_f32_dpp v215, v59, v135 row_shl:15 row_mask:0xf bank_mask:0xf
	v_fmac_f32_dpp v208, v52, v136 row_shr:2 row_mask:0xf bank_mask:0xf
	v_fmac_f32_dpp v209, v53, v137 row_shr:2 row_mask:0xf bank_mask:0xf
	v_fmac_f32_dpp v210, v54, v138 row_shr:2 row_mask:0xf bank_mask:0xf
	v_fmac_f32_dpp v211, v55, v139 row_shr:2 row_mask:0xf bank_mask:0xf
	v_fmac_f32_dpp v212, v40, v128 row_shr:2 row_mask:0xf bank_mask:0xf
	v_fmac_f32_dpp v213, v41, v129 row_shr:2 row_mask:0xf bank_mask:0xf
	v_fmac_f32_dpp v214, v42, v130 row_shr:2 row_mask:0xf bank_mask:0xf
	v_fmac_f32_dpp v215, v43, v131 row_shr:2 row_mask:0xf bank_mask:0xf
	v_fmac_f32_dpp v208, v60, v136 row_shl:14 row_mask:0xf bank_mask:0xf
	v_fmac_f32_dpp v209, v61, v137 row_shl:14 row_mask:0xf bank_mask:0xf
	v_fmac_f32_dpp v210, v62, v138 row_shl:14 row_mask:0xf bank_mask:0xf
	v_fmac_f32_dpp v211, v63, v139 row_shl:14 row_mask:0xf bank_mask:0xf
	v_fmac_f32_dpp v212, v56, v128 row_shl:14 row_mask:0xf bank_mask:0xf
	v_fmac_f32_dpp v213, v57, v129 row_shl:14 row_mask:0xf bank_mask:0xf
	v_fmac_f32_dpp v214, v58, v130 row_shl:14 row_mask:0xf bank_mask:0xf
	v_fmac_f32_dpp v215, v59, v131 row_shl:14 row_mask:0xf bank_mask:0xf
	v_mul_f32_e32 v216, 0xbfb8aa3b, v208
	v_mul_f32_e32 v217, 0xbfb8aa3b, v209
	v_mul_f32_e32 v218, 0xbfb8aa3b, v210
	v_mul_f32_e32 v219, 0xbfb8aa3b, v211
	v_exp_f32_e32 v216, v216
	v_exp_f32_e32 v217, v217
	v_exp_f32_e32 v218, v218
	v_exp_f32_e32 v219, v219
	v_add_f32_e32 v216, 1.0, v216
	v_add_f32_e32 v217, 1.0, v217
	v_add_f32_e32 v218, 1.0, v218
	v_add_f32_e32 v219, 1.0, v219
	v_rcp_f32_e32 v216, v216
	v_rcp_f32_e32 v217, v217
	v_rcp_f32_e32 v218, v218
	v_rcp_f32_e32 v219, v219
	s_mov_b32 s80, 0x16000
	s_mov_b32 s81, 0
	v_lshl_add_u64 v[222:223], v[224:225], 0, s[80:81]
	v_pk_mul_f32 v[208:209], v[208:209], v[216:217]
	v_pk_mul_f32 v[210:211], v[210:211], v[218:219]
	v_pk_mul_f32 v[208:209], v[212:213], v[208:209]
	v_pk_mul_f32 v[210:211], v[214:215], v[210:211]
	v_cvt_pk_bf16_f32 v220, v208, v209
	v_cvt_pk_bf16_f32 v221, v210, v211
	global_store_dwordx2 v[222:223], v[220:221], off
	v_pk_fma_f32 v[160:161], v[152:153], v[36:37], v[156:157]
	v_pk_fma_f32 v[162:163], v[154:155], v[38:39], v[158:159]
	v_pk_fma_f32 v[164:165], v[144:145], v[16:17], v[148:149]
	v_pk_fma_f32 v[166:167], v[146:147], v[18:19], v[150:151]
	v_fmac_f32_dpp v160, v36, v140 row_shr:1 row_mask:0xf bank_mask:0xf
	v_fmac_f32_dpp v161, v37, v141 row_shr:1 row_mask:0xf bank_mask:0xf
	v_fmac_f32_dpp v162, v38, v142 row_shr:1 row_mask:0xf bank_mask:0xf
	v_fmac_f32_dpp v163, v39, v143 row_shr:1 row_mask:0xf bank_mask:0xf
	v_fmac_f32_dpp v164, v16, v132 row_shr:1 row_mask:0xf bank_mask:0xf
	v_fmac_f32_dpp v165, v17, v133 row_shr:1 row_mask:0xf bank_mask:0xf
	v_fmac_f32_dpp v166, v18, v134 row_shr:1 row_mask:0xf bank_mask:0xf
	v_fmac_f32_dpp v167, v19, v135 row_shr:1 row_mask:0xf bank_mask:0xf
	v_fmac_f32_dpp v160, v52, v140 row_shl:15 row_mask:0xf bank_mask:0xf
	v_fmac_f32_dpp v161, v53, v141 row_shl:15 row_mask:0xf bank_mask:0xf
	v_fmac_f32_dpp v162, v54, v142 row_shl:15 row_mask:0xf bank_mask:0xf
	v_fmac_f32_dpp v163, v55, v143 row_shl:15 row_mask:0xf bank_mask:0xf
	v_fmac_f32_dpp v164, v40, v132 row_shl:15 row_mask:0xf bank_mask:0xf
	v_fmac_f32_dpp v165, v41, v133 row_shl:15 row_mask:0xf bank_mask:0xf
	v_fmac_f32_dpp v166, v42, v134 row_shl:15 row_mask:0xf bank_mask:0xf
	v_fmac_f32_dpp v167, v43, v135 row_shl:15 row_mask:0xf bank_mask:0xf
	v_fmac_f32_dpp v160, v36, v136 row_shr:2 row_mask:0xf bank_mask:0xf
	v_fmac_f32_dpp v161, v37, v137 row_shr:2 row_mask:0xf bank_mask:0xf
	v_fmac_f32_dpp v162, v38, v138 row_shr:2 row_mask:0xf bank_mask:0xf
	v_fmac_f32_dpp v163, v39, v139 row_shr:2 row_mask:0xf bank_mask:0xf
	v_fmac_f32_dpp v164, v16, v128 row_shr:2 row_mask:0xf bank_mask:0xf
; DI float silu_fast(float x) { return x * __builtin_amdgcn_rcpf(1.f + __expf(-x)); }
; template <int CTRL> DI float dppf(float v) { return __builtin_bit_cast(float, __builtin_amdgcn_update_dpp(0, __builtin_bit_cast(int, v), CTRL, 0xf, 0xf, true)); }
; DI void Epi::fused(const f32x4 (&acc)[2][2][4][2], int pm, int pn, int wr, int wc, int fr, int fq) const {
;     ...
;             for (int m = 0; m < 4; ++m) {
;                 const f32x4 ca = acc[ai][bj][m][0], cb = acc[ai][bj][m][1];
;                 const int row = pm * 256 + ai * 128 + wr * 64 + m * 16 + fr;
;                 float o[4];
; #pragma unroll
;                 for (int e = 0; e < 4; ++e) {
;                     const float a1 = dppf<0x111>(ca[e]) + dppf<0x10F>(pa[e]), a2 = dppf<0x112>(ca[e]) + dppf<0x10E>(pa[e]);
;                     const float b1 = dppf<0x111>(cb[e]) + dppf<0x10F>(pb[e]), b2 = dppf<0x112>(cb[e]) + dppf<0x10E>(pb[e]);
;                     const float ya = fmaf(wa0[e], a2, fmaf(wa1[e], a1, fmaf(wa2[e], ca[e], ba[e])));
;                     const float yb = fmaf(wb0[e], b2, fmaf(wb1[e], b1, fmaf(wb2[e], cb[e], bb[e])));
;                     o[e] = silu_fast(ya) * yb; }
;                 if (m > 0 || fr >= 2) { u32x2 w; w.x = pk2(o[0], o[1]); w.y = pk2(o[2], o[3]); *(u32x2*)(E.d0 + (size_t)row * FFH + j0) = w; }
;                 if ((m == 0 && fr < 2) || (m == 3 && fr >= 14)) { float* hb = E.f0 + ((size_t)(row >> 6) * 4 + (m == 0 ? fr : fr - 12)) * FF2 + ncol; *(f32x4*)hb = ca; *(f32x4*)(hb + 4) = cb; }
;                 pa = ca; pb = cb;
	v_fmac_f32_dpp v165, v17, v129 row_shr:2 row_mask:0xf bank_mask:0xf
	v_fmac_f32_dpp v166, v18, v130 row_shr:2 row_mask:0xf bank_mask:0xf
	v_fmac_f32_dpp v167, v19, v131 row_shr:2 row_mask:0xf bank_mask:0xf
	v_fmac_f32_dpp v160, v52, v136 row_shl:14 row_mask:0xf bank_mask:0xf
	v_fmac_f32_dpp v161, v53, v137 row_shl:14 row_mask:0xf bank_mask:0xf
	v_fmac_f32_dpp v162, v54, v138 row_shl:14 row_mask:0xf bank_mask:0xf
	v_fmac_f32_dpp v163, v55, v139 row_shl:14 row_mask:0xf bank_mask:0xf
	v_fmac_f32_dpp v164, v40, v128 row_shl:14 row_mask:0xf bank_mask:0xf
	v_fmac_f32_dpp v165, v41, v129 row_shl:14 row_mask:0xf bank_mask:0xf
	v_fmac_f32_dpp v166, v42, v130 row_shl:14 row_mask:0xf bank_mask:0xf
	v_fmac_f32_dpp v167, v43, v131 row_shl:14 row_mask:0xf bank_mask:0xf
	v_mul_f32_e32 v168, 0xbfb8aa3b, v160
	v_mul_f32_e32 v169, 0xbfb8aa3b, v161
	v_mul_f32_e32 v170, 0xbfb8aa3b, v162
	v_mul_f32_e32 v171, 0xbfb8aa3b, v163
	v_exp_f32_e32 v168, v168
	v_exp_f32_e32 v169, v169
	v_exp_f32_e32 v170, v170
	v_exp_f32_e32 v171, v171
	v_add_f32_e32 v168, 1.0, v168
	v_add_f32_e32 v169, 1.0, v169
	v_add_f32_e32 v170, 1.0, v170
	v_add_f32_e32 v171, 1.0, v171
	v_rcp_f32_e32 v168, v168
	v_rcp_f32_e32 v169, v169
	v_rcp_f32_e32 v170, v170
	v_rcp_f32_e32 v171, v171
	s_mov_b32 s80, 0x2c000
	s_mov_b32 s81, 0
	v_lshl_add_u64 v[174:175], v[224:225], 0, s[80:81]
	v_pk_mul_f32 v[160:161], v[160:161], v[168:169]
	v_pk_mul_f32 v[162:163], v[162:163], v[170:171]
	v_pk_mul_f32 v[160:161], v[164:165], v[160:161]
	v_pk_mul_f32 v[162:163], v[166:167], v[162:163]
	v_cvt_pk_bf16_f32 v172, v160, v161
	v_cvt_pk_bf16_f32 v173, v162, v163
	global_store_dwordx2 v[174:175], v[172:173], off
	v_pk_fma_f32 v[208:209], v[152:153], v[12:13], v[156:157]
	v_pk_fma_f32 v[210:211], v[154:155], v[14:15], v[158:159]
	v_pk_fma_f32 v[212:213], v[144:145], v[0:1], v[148:149]
	v_pk_fma_f32 v[214:215], v[146:147], v[2:3], v[150:151]
	v_fmac_f32_dpp v208, v12, v140 row_shr:1 row_mask:0xf bank_mask:0xf
	v_fmac_f32_dpp v209, v13, v141 row_shr:1 row_mask:0xf bank_mask:0xf
	v_fmac_f32_dpp v210, v14, v142 row_shr:1 row_mask:0xf bank_mask:0xf
	v_fmac_f32_dpp v211, v15, v143 row_shr:1 row_mask:0xf bank_mask:0xf
	v_fmac_f32_dpp v212, v0, v132 row_shr:1 row_mask:0xf bank_mask:0xf
	v_fmac_f32_dpp v213, v1, v133 row_shr:1 row_mask:0xf bank_mask:0xf
	v_fmac_f32_dpp v214, v2, v134 row_shr:1 row_mask:0xf bank_mask:0xf
	v_fmac_f32_dpp v215, v3, v135 row_shr:1 row_mask:0xf bank_mask:0xf
	v_fmac_f32_dpp v208, v36, v140 row_shl:15 row_mask:0xf bank_mask:0xf
	v_fmac_f32_dpp v209, v37, v141 row_shl:15 row_mask:0xf bank_mask:0xf
	v_fmac_f32_dpp v210, v38, v142 row_shl:15 row_mask:0xf bank_mask:0xf
	v_fmac_f32_dpp v211, v39, v143 row_shl:15 row_mask:0xf bank_mask:0xf
	v_fmac_f32_dpp v212, v16, v132 row_shl:15 row_mask:0xf bank_mask:0xf
	v_fmac_f32_dpp v213, v17, v133 row_shl:15 row_mask:0xf bank_mask:0xf
	v_fmac_f32_dpp v214, v18, v134 row_shl:15 row_mask:0xf bank_mask:0xf
	v_fmac_f32_dpp v215, v19, v135 row_shl:15 row_mask:0xf bank_mask:0xf
	v_fmac_f32_dpp v208, v12, v136 row_shr:2 row_mask:0xf bank_mask:0xf
	v_fmac_f32_dpp v209, v13, v137 row_shr:2 row_mask:0xf bank_mask:0xf
	v_fmac_f32_dpp v210, v14, v138 row_shr:2 row_mask:0xf bank_mask:0xf
	v_fmac_f32_dpp v211, v15, v139 row_shr:2 row_mask:0xf bank_mask:0xf
	v_fmac_f32_dpp v212, v0, v128 row_shr:2 row_mask:0xf bank_mask:0xf
	v_fmac_f32_dpp v213, v1, v129 row_shr:2 row_mask:0xf bank_mask:0xf
	v_fmac_f32_dpp v214, v2, v130 row_shr:2 row_mask:0xf bank_mask:0xf
	v_fmac_f32_dpp v215, v3, v131 row_shr:2 row_mask:0xf bank_mask:0xf
	v_fmac_f32_dpp v208, v36, v136 row_shl:14 row_mask:0xf bank_mask:0xf
	v_fmac_f32_dpp v209, v37, v137 row_shl:14 row_mask:0xf bank_mask:0xf
	v_fmac_f32_dpp v210, v38, v138 row_shl:14 row_mask:0xf bank_mask:0xf
	v_fmac_f32_dpp v211, v39, v139 row_shl:14 row_mask:0xf bank_mask:0xf
	v_fmac_f32_dpp v212, v16, v128 row_shl:14 row_mask:0xf bank_mask:0xf
	v_fmac_f32_dpp v213, v17, v129 row_shl:14 row_mask:0xf bank_mask:0xf
	v_fmac_f32_dpp v214, v18, v130 row_shl:14 row_mask:0xf bank_mask:0xf
	v_fmac_f32_dpp v215, v19, v131 row_shl:14 row_mask:0xf bank_mask:0xf
	v_mul_f32_e32 v216, 0xbfb8aa3b, v208
	v_mul_f32_e32 v217, 0xbfb8aa3b, v209
	v_mul_f32_e32 v218, 0xbfb8aa3b, v210
	v_mul_f32_e32 v219, 0xbfb8aa3b, v211
	v_exp_f32_e32 v216, v216
	v_exp_f32_e32 v217, v217
	v_exp_f32_e32 v218, v218
	v_exp_f32_e32 v219, v219
	v_add_f32_e32 v216, 1.0, v216
	v_add_f32_e32 v217, 1.0, v217
	v_add_f32_e32 v218, 1.0, v218
	v_add_f32_e32 v219, 1.0, v219
	v_rcp_f32_e32 v216, v216
	v_rcp_f32_e32 v217, v217
	v_rcp_f32_e32 v218, v218
	v_rcp_f32_e32 v219, v219
	s_mov_b32 s80, 0x42000
	s_mov_b32 s81, 0
	v_lshl_add_u64 v[222:223], v[224:225], 0, s[80:81]
	v_pk_mul_f32 v[208:209], v[208:209], v[216:217]
	v_pk_mul_f32 v[210:211], v[210:211], v[218:219]
	v_pk_mul_f32 v[208:209], v[212:213], v[208:209]
	v_pk_mul_f32 v[210:211], v[214:215], v[210:211]
	v_cvt_pk_bf16_f32 v220, v208, v209
	v_cvt_pk_bf16_f32 v221, v210, v211
	global_store_dwordx2 v[222:223], v[220:221], off
	s_ashr_i32 s80, s71, 6
	s_lshl_b32 s80, s80, 2
	s_add_i32 s80, s80, 8
	v_add_u32_e32 v226, s80, v190
	v_mov_b64_e32 v[222:223], s[8:9]
	s_movk_i32 s80, 0x5800
	v_mad_i64_i32 v[222:223], s[78:79], v226, s80, v[222:223]
	v_lshl_add_u64 v[222:223], v[228:229], 2, v[222:223]
	s_and_saveexec_b64 s[76:77], s[42:43]
	global_store_dwordx4 v[222:223], v[12:15], off
	global_store_dwordx4 v[222:223], v[0:3], off offset:16
	s_or_b64 exec, exec, s[76:77]
	v_mov_b32_e32 v228, v199
	v_mov_b64_e32 v[224:225], s[12:13]
	s_movk_i32 s80, 0x1600
	v_mad_i64_i32 v[224:225], s[78:79], v228, s80, v[224:225]
	v_add_u32_e32 v228, 128, v240
	v_mov_b32_e32 v229, 0
	v_lshl_add_u64 v[224:225], v[228:229], 0, v[224:225]
	s_waitcnt vmcnt(8)
; DI float silu_fast(float x) { return x * __builtin_amdgcn_rcpf(1.f + __expf(-x)); }
; template <int CTRL> DI float dppf(float v) { return __builtin_bit_cast(float, __builtin_amdgcn_update_dpp(0, __builtin_bit_cast(int, v), CTRL, 0xf, 0xf, true)); }
; DI void Epi::fused(const f32x4 (&acc)[2][2][4][2], int pm, int pn, int wr, int wc, int fr, int fq) const {
;     ...
;             for (int m = 0; m < 4; ++m) {
;                 const f32x4 ca = acc[ai][bj][m][0], cb = acc[ai][bj][m][1];
;                 const int row = pm * 256 + ai * 128 + wr * 64 + m * 16 + fr;
;                 float o[4];
; #pragma unroll
;                 for (int e = 0; e < 4; ++e) {
;                     const float a1 = dppf<0x111>(ca[e]) + dppf<0x10F>(pa[e]), a2 = dppf<0x112>(ca[e]) + dppf<0x10E>(pa[e]);
;                     const float b1 = dppf<0x111>(cb[e]) + dppf<0x10F>(pb[e]), b2 = dppf<0x112>(cb[e]) + dppf<0x10E>(pb[e]);
;                     const float ya = fmaf(wa0[e], a2, fmaf(wa1[e], a1, fmaf(wa2[e], ca[e], ba[e])));
;                     const float yb = fmaf(wb0[e], b2, fmaf(wb1[e], b1, fmaf(wb2[e], cb[e], bb[e])));
;                     o[e] = silu_fast(ya) * yb; }
;                 if (m > 0 || fr >= 2) { u32x2 w; w.x = pk2(o[0], o[1]); w.y = pk2(o[2], o[3]); *(u32x2*)(E.d0 + (size_t)row * FFH + j0) = w; }
;                 if ((m == 0 && fr < 2) || (m == 3 && fr >= 14)) { float* hb = E.f0 + ((size_t)(row >> 6) * 4 + (m == 0 ? fr : fr - 12)) * FF2 + ncol; *(f32x4*)hb = ca; *(f32x4*)(hb + 4) = cb; }
;                 pa = ca; pb = cb;
	v_pk_fma_f32 v[160:161], v[100:101], v[112:113], v[124:125]
	v_pk_fma_f32 v[162:163], v[102:103], v[114:115], v[126:127]
	v_pk_fma_f32 v[164:165], v[120:121], v[108:109], v[72:73]
	v_pk_fma_f32 v[166:167], v[122:123], v[110:111], v[74:75]
	v_fmac_f32_dpp v160, v112, v88 row_shr:1 row_mask:0xf bank_mask:0xf
	v_fmac_f32_dpp v161, v113, v89 row_shr:1 row_mask:0xf bank_mask:0xf
	v_fmac_f32_dpp v162, v114, v90 row_shr:1 row_mask:0xf bank_mask:0xf
	v_fmac_f32_dpp v163, v115, v91 row_shr:1 row_mask:0xf bank_mask:0xf
	v_fmac_f32_dpp v164, v108, v116 row_shr:1 row_mask:0xf bank_mask:0xf
	v_fmac_f32_dpp v165, v109, v117 row_shr:1 row_mask:0xf bank_mask:0xf
	v_fmac_f32_dpp v166, v110, v118 row_shr:1 row_mask:0xf bank_mask:0xf
	v_fmac_f32_dpp v167, v111, v119 row_shr:1 row_mask:0xf bank_mask:0xf
	v_fmac_f32_dpp v160, v112, v84 row_shr:2 row_mask:0xf bank_mask:0xf
	v_fmac_f32_dpp v161, v113, v85 row_shr:2 row_mask:0xf bank_mask:0xf
	v_fmac_f32_dpp v162, v114, v86 row_shr:2 row_mask:0xf bank_mask:0xf
	v_fmac_f32_dpp v163, v115, v87 row_shr:2 row_mask:0xf bank_mask:0xf
	v_fmac_f32_dpp v164, v108, v104 row_shr:2 row_mask:0xf bank_mask:0xf
	v_fmac_f32_dpp v165, v109, v105 row_shr:2 row_mask:0xf bank_mask:0xf
	v_fmac_f32_dpp v166, v110, v106 row_shr:2 row_mask:0xf bank_mask:0xf
	v_fmac_f32_dpp v167, v111, v107 row_shr:2 row_mask:0xf bank_mask:0xf
	v_mul_f32_e32 v168, 0xbfb8aa3b, v160
	v_mul_f32_e32 v169, 0xbfb8aa3b, v161
	v_mul_f32_e32 v170, 0xbfb8aa3b, v162
	v_mul_f32_e32 v171, 0xbfb8aa3b, v163
	v_exp_f32_e32 v168, v168
	v_exp_f32_e32 v169, v169
	v_exp_f32_e32 v170, v170
	v_exp_f32_e32 v171, v171
	v_add_f32_e32 v168, 1.0, v168
	v_add_f32_e32 v169, 1.0, v169
	v_add_f32_e32 v170, 1.0, v170
	v_add_f32_e32 v171, 1.0, v171
	v_rcp_f32_e32 v168, v168
	v_rcp_f32_e32 v169, v169
	v_rcp_f32_e32 v170, v170
	v_rcp_f32_e32 v171, v171
	v_mov_b64_e32 v[174:175], v[224:225]
	v_pk_mul_f32 v[160:161], v[160:161], v[168:169]
	v_pk_mul_f32 v[162:163], v[162:163], v[170:171]
	v_pk_mul_f32 v[160:161], v[164:165], v[160:161]
	v_pk_mul_f32 v[162:163], v[166:167], v[162:163]
	v_cvt_pk_bf16_f32 v172, v160, v161
	v_cvt_pk_bf16_f32 v173, v162, v163
	s_and_saveexec_b64 s[76:77], s[38:39]
	global_store_dwordx2 v[174:175], v[172:173], off
	s_or_b64 exec, exec, s[76:77]
	s_ashr_i32 s80, s71, 6
	s_lshl_b32 s80, s80, 2
	v_add_u32_e32 v226, s80, v188
	v_mov_b64_e32 v[174:175], s[8:9]
	s_movk_i32 s80, 0x5800
	v_mad_i64_i32 v[174:175], s[78:79], v226, s80, v[174:175]
	v_lshl_add_u64 v[174:175], v[228:229], 2, v[174:175]
	s_and_saveexec_b64 s[76:77], s[40:41]
	global_store_dwordx4 v[174:175], v[112:115], off
	global_store_dwordx4 v[174:175], v[108:111], off offset:16
	s_or_b64 exec, exec, s[76:77]
	v_pk_fma_f32 v[208:209], v[100:101], v[96:97], v[124:125]
	v_pk_fma_f32 v[210:211], v[102:103], v[98:99], v[126:127]
	v_pk_fma_f32 v[212:213], v[120:121], v[92:93], v[72:73]
	v_pk_fma_f32 v[214:215], v[122:123], v[94:95], v[74:75]
	v_fmac_f32_dpp v208, v96, v88 row_shr:1 row_mask:0xf bank_mask:0xf
	v_fmac_f32_dpp v209, v97, v89 row_shr:1 row_mask:0xf bank_mask:0xf
	v_fmac_f32_dpp v210, v98, v90 row_shr:1 row_mask:0xf bank_mask:0xf
	v_fmac_f32_dpp v211, v99, v91 row_shr:1 row_mask:0xf bank_mask:0xf
	v_fmac_f32_dpp v212, v92, v116 row_shr:1 row_mask:0xf bank_mask:0xf
	v_fmac_f32_dpp v213, v93, v117 row_shr:1 row_mask:0xf bank_mask:0xf
	v_fmac_f32_dpp v214, v94, v118 row_shr:1 row_mask:0xf bank_mask:0xf
	v_fmac_f32_dpp v215, v95, v119 row_shr:1 row_mask:0xf bank_mask:0xf
	v_fmac_f32_dpp v208, v112, v88 row_shl:15 row_mask:0xf bank_mask:0xf
	v_fmac_f32_dpp v209, v113, v89 row_shl:15 row_mask:0xf bank_mask:0xf
	v_fmac_f32_dpp v210, v114, v90 row_shl:15 row_mask:0xf bank_mask:0xf
	v_fmac_f32_dpp v211, v115, v91 row_shl:15 row_mask:0xf bank_mask:0xf
	v_fmac_f32_dpp v212, v108, v116 row_shl:15 row_mask:0xf bank_mask:0xf
	v_fmac_f32_dpp v213, v109, v117 row_shl:15 row_mask:0xf bank_mask:0xf
	v_fmac_f32_dpp v214, v110, v118 row_shl:15 row_mask:0xf bank_mask:0xf
	v_fmac_f32_dpp v215, v111, v119 row_shl:15 row_mask:0xf bank_mask:0xf
	v_fmac_f32_dpp v208, v96, v84 row_shr:2 row_mask:0xf bank_mask:0xf
	v_fmac_f32_dpp v209, v97, v85 row_shr:2 row_mask:0xf bank_mask:0xf
	v_fmac_f32_dpp v210, v98, v86 row_shr:2 row_mask:0xf bank_mask:0xf
	v_fmac_f32_dpp v211, v99, v87 row_shr:2 row_mask:0xf bank_mask:0xf
	v_fmac_f32_dpp v212, v92, v104 row_shr:2 row_mask:0xf bank_mask:0xf
	v_fmac_f32_dpp v213, v93, v105 row_shr:2 row_mask:0xf bank_mask:0xf
	v_fmac_f32_dpp v214, v94, v106 row_shr:2 row_mask:0xf bank_mask:0xf
	v_fmac_f32_dpp v215, v95, v107 row_shr:2 row_mask:0xf bank_mask:0xf
	v_fmac_f32_dpp v208, v112, v84 row_shl:14 row_mask:0xf bank_mask:0xf
	v_fmac_f32_dpp v209, v113, v85 row_shl:14 row_mask:0xf bank_mask:0xf
	v_fmac_f32_dpp v210, v114, v86 row_shl:14 row_mask:0xf bank_mask:0xf
	v_fmac_f32_dpp v211, v115, v87 row_shl:14 row_mask:0xf bank_mask:0xf
	v_fmac_f32_dpp v212, v108, v104 row_shl:14 row_mask:0xf bank_mask:0xf
	v_fmac_f32_dpp v213, v109, v105 row_shl:14 row_mask:0xf bank_mask:0xf
	v_fmac_f32_dpp v214, v110, v106 row_shl:14 row_mask:0xf bank_mask:0xf
	v_fmac_f32_dpp v215, v111, v107 row_shl:14 row_mask:0xf bank_mask:0xf
	v_mul_f32_e32 v216, 0xbfb8aa3b, v208
	v_mul_f32_e32 v217, 0xbfb8aa3b, v209
	v_mul_f32_e32 v218, 0xbfb8aa3b, v210
	v_mul_f32_e32 v219, 0xbfb8aa3b, v211
	v_exp_f32_e32 v216, v216
	v_exp_f32_e32 v217, v217
	v_exp_f32_e32 v218, v218
	v_exp_f32_e32 v219, v219
	v_add_f32_e32 v216, 1.0, v216
	v_add_f32_e32 v217, 1.0, v217
	v_add_f32_e32 v218, 1.0, v218
	v_add_f32_e32 v219, 1.0, v219
	v_rcp_f32_e32 v216, v216
	v_rcp_f32_e32 v217, v217
	v_rcp_f32_e32 v218, v218
	v_rcp_f32_e32 v219, v219
; DI float silu_fast(float x) { return x * __builtin_amdgcn_rcpf(1.f + __expf(-x)); }
; template <int CTRL> DI float dppf(float v) { return __builtin_bit_cast(float, __builtin_amdgcn_update_dpp(0, __builtin_bit_cast(int, v), CTRL, 0xf, 0xf, true)); }
; DI void Epi::fused(const f32x4 (&acc)[2][2][4][2], int pm, int pn, int wr, int wc, int fr, int fq) const {
;     ...
;             for (int m = 0; m < 4; ++m) {
;                 const f32x4 ca = acc[ai][bj][m][0], cb = acc[ai][bj][m][1];
;                 const int row = pm * 256 + ai * 128 + wr * 64 + m * 16 + fr;
;                 float o[4];
; #pragma unroll
;                 for (int e = 0; e < 4; ++e) {
;                     const float a1 = dppf<0x111>(ca[e]) + dppf<0x10F>(pa[e]), a2 = dppf<0x112>(ca[e]) + dppf<0x10E>(pa[e]);
;                     const float b1 = dppf<0x111>(cb[e]) + dppf<0x10F>(pb[e]), b2 = dppf<0x112>(cb[e]) + dppf<0x10E>(pb[e]);
;                     const float ya = fmaf(wa0[e], a2, fmaf(wa1[e], a1, fmaf(wa2[e], ca[e], ba[e])));
;                     const float yb = fmaf(wb0[e], b2, fmaf(wb1[e], b1, fmaf(wb2[e], cb[e], bb[e])));
;                     o[e] = silu_fast(ya) * yb; }
;                 if (m > 0 || fr >= 2) { u32x2 w; w.x = pk2(o[0], o[1]); w.y = pk2(o[2], o[3]); *(u32x2*)(E.d0 + (size_t)row * FFH + j0) = w; }
;                 if ((m == 0 && fr < 2) || (m == 3 && fr >= 14)) { float* hb = E.f0 + ((size_t)(row >> 6) * 4 + (m == 0 ? fr : fr - 12)) * FF2 + ncol; *(f32x4*)hb = ca; *(f32x4*)(hb + 4) = cb; }
;                 pa = ca; pb = cb;
	s_mov_b32 s80, 0x16000
	s_mov_b32 s81, 0
	v_lshl_add_u64 v[222:223], v[224:225], 0, s[80:81]
	v_pk_mul_f32 v[208:209], v[208:209], v[216:217]
	v_pk_mul_f32 v[210:211], v[210:211], v[218:219]
	v_pk_mul_f32 v[208:209], v[212:213], v[208:209]
	v_pk_mul_f32 v[210:211], v[214:215], v[210:211]
	v_cvt_pk_bf16_f32 v220, v208, v209
	v_cvt_pk_bf16_f32 v221, v210, v211
	global_store_dwordx2 v[222:223], v[220:221], off
	v_pk_fma_f32 v[160:161], v[100:101], v[80:81], v[124:125]
	v_pk_fma_f32 v[162:163], v[102:103], v[82:83], v[126:127]
	v_pk_fma_f32 v[164:165], v[120:121], v[76:77], v[72:73]
	v_pk_fma_f32 v[166:167], v[122:123], v[78:79], v[74:75]
	v_fmac_f32_dpp v160, v80, v88 row_shr:1 row_mask:0xf bank_mask:0xf
	v_fmac_f32_dpp v161, v81, v89 row_shr:1 row_mask:0xf bank_mask:0xf
	v_fmac_f32_dpp v162, v82, v90 row_shr:1 row_mask:0xf bank_mask:0xf
	v_fmac_f32_dpp v163, v83, v91 row_shr:1 row_mask:0xf bank_mask:0xf
	v_fmac_f32_dpp v164, v76, v116 row_shr:1 row_mask:0xf bank_mask:0xf
	v_fmac_f32_dpp v165, v77, v117 row_shr:1 row_mask:0xf bank_mask:0xf
	v_fmac_f32_dpp v166, v78, v118 row_shr:1 row_mask:0xf bank_mask:0xf
	v_fmac_f32_dpp v167, v79, v119 row_shr:1 row_mask:0xf bank_mask:0xf
	v_fmac_f32_dpp v160, v96, v88 row_shl:15 row_mask:0xf bank_mask:0xf
	v_fmac_f32_dpp v161, v97, v89 row_shl:15 row_mask:0xf bank_mask:0xf
	v_fmac_f32_dpp v162, v98, v90 row_shl:15 row_mask:0xf bank_mask:0xf
	v_fmac_f32_dpp v163, v99, v91 row_shl:15 row_mask:0xf bank_mask:0xf
	v_fmac_f32_dpp v164, v92, v116 row_shl:15 row_mask:0xf bank_mask:0xf
	v_fmac_f32_dpp v165, v93, v117 row_shl:15 row_mask:0xf bank_mask:0xf
	v_fmac_f32_dpp v166, v94, v118 row_shl:15 row_mask:0xf bank_mask:0xf
	v_fmac_f32_dpp v167, v95, v119 row_shl:15 row_mask:0xf bank_mask:0xf
	v_fmac_f32_dpp v160, v80, v84 row_shr:2 row_mask:0xf bank_mask:0xf
	v_fmac_f32_dpp v161, v81, v85 row_shr:2 row_mask:0xf bank_mask:0xf
	v_fmac_f32_dpp v162, v82, v86 row_shr:2 row_mask:0xf bank_mask:0xf
	v_fmac_f32_dpp v163, v83, v87 row_shr:2 row_mask:0xf bank_mask:0xf
	v_fmac_f32_dpp v164, v76, v104 row_shr:2 row_mask:0xf bank_mask:0xf
	v_fmac_f32_dpp v165, v77, v105 row_shr:2 row_mask:0xf bank_mask:0xf
	v_fmac_f32_dpp v166, v78, v106 row_shr:2 row_mask:0xf bank_mask:0xf
	v_fmac_f32_dpp v167, v79, v107 row_shr:2 row_mask:0xf bank_mask:0xf
	v_fmac_f32_dpp v160, v96, v84 row_shl:14 row_mask:0xf bank_mask:0xf
	v_fmac_f32_dpp v161, v97, v85 row_shl:14 row_mask:0xf bank_mask:0xf
	v_fmac_f32_dpp v162, v98, v86 row_shl:14 row_mask:0xf bank_mask:0xf
	v_fmac_f32_dpp v163, v99, v87 row_shl:14 row_mask:0xf bank_mask:0xf
	v_fmac_f32_dpp v164, v92, v104 row_shl:14 row_mask:0xf bank_mask:0xf
	v_fmac_f32_dpp v165, v93, v105 row_shl:14 row_mask:0xf bank_mask:0xf
	v_fmac_f32_dpp v166, v94, v106 row_shl:14 row_mask:0xf bank_mask:0xf
	v_fmac_f32_dpp v167, v95, v107 row_shl:14 row_mask:0xf bank_mask:0xf
	v_mul_f32_e32 v168, 0xbfb8aa3b, v160
	v_mul_f32_e32 v169, 0xbfb8aa3b, v161
	v_mul_f32_e32 v170, 0xbfb8aa3b, v162
	v_mul_f32_e32 v171, 0xbfb8aa3b, v163
	v_exp_f32_e32 v168, v168
	v_exp_f32_e32 v169, v169
	v_exp_f32_e32 v170, v170
	v_exp_f32_e32 v171, v171
	v_add_f32_e32 v168, 1.0, v168
	v_add_f32_e32 v169, 1.0, v169
	v_add_f32_e32 v170, 1.0, v170
	v_add_f32_e32 v171, 1.0, v171
	v_rcp_f32_e32 v168, v168
	v_rcp_f32_e32 v169, v169
	v_rcp_f32_e32 v170, v170
	v_rcp_f32_e32 v171, v171
	s_mov_b32 s80, 0x2c000
	s_mov_b32 s81, 0
	v_lshl_add_u64 v[174:175], v[224:225], 0, s[80:81]
	v_pk_mul_f32 v[160:161], v[160:161], v[168:169]
	v_pk_mul_f32 v[162:163], v[162:163], v[170:171]
	v_pk_mul_f32 v[160:161], v[164:165], v[160:161]
	v_pk_mul_f32 v[162:163], v[166:167], v[162:163]
	v_cvt_pk_bf16_f32 v172, v160, v161
	v_cvt_pk_bf16_f32 v173, v162, v163
	global_store_dwordx2 v[174:175], v[172:173], off
	v_pk_fma_f32 v[208:209], v[100:101], v[68:69], v[124:125]
	v_pk_fma_f32 v[210:211], v[102:103], v[70:71], v[126:127]
	v_pk_fma_f32 v[212:213], v[120:121], v[64:65], v[72:73]
	v_pk_fma_f32 v[214:215], v[122:123], v[66:67], v[74:75]
	v_fmac_f32_dpp v208, v68, v88 row_shr:1 row_mask:0xf bank_mask:0xf
	v_fmac_f32_dpp v209, v69, v89 row_shr:1 row_mask:0xf bank_mask:0xf
	v_fmac_f32_dpp v210, v70, v90 row_shr:1 row_mask:0xf bank_mask:0xf
	v_fmac_f32_dpp v211, v71, v91 row_shr:1 row_mask:0xf bank_mask:0xf
	v_fmac_f32_dpp v212, v64, v116 row_shr:1 row_mask:0xf bank_mask:0xf
	v_fmac_f32_dpp v213, v65, v117 row_shr:1 row_mask:0xf bank_mask:0xf
	v_fmac_f32_dpp v214, v66, v118 row_shr:1 row_mask:0xf bank_mask:0xf
	v_fmac_f32_dpp v215, v67, v119 row_shr:1 row_mask:0xf bank_mask:0xf
	v_fmac_f32_dpp v208, v80, v88 row_shl:15 row_mask:0xf bank_mask:0xf
	v_fmac_f32_dpp v209, v81, v89 row_shl:15 row_mask:0xf bank_mask:0xf
	v_fmac_f32_dpp v210, v82, v90 row_shl:15 row_mask:0xf bank_mask:0xf
	v_fmac_f32_dpp v211, v83, v91 row_shl:15 row_mask:0xf bank_mask:0xf
	v_fmac_f32_dpp v212, v76, v116 row_shl:15 row_mask:0xf bank_mask:0xf
	v_fmac_f32_dpp v213, v77, v117 row_shl:15 row_mask:0xf bank_mask:0xf
	v_fmac_f32_dpp v214, v78, v118 row_shl:15 row_mask:0xf bank_mask:0xf
	v_fmac_f32_dpp v215, v79, v119 row_shl:15 row_mask:0xf bank_mask:0xf
	v_fmac_f32_dpp v208, v68, v84 row_shr:2 row_mask:0xf bank_mask:0xf
	v_fmac_f32_dpp v209, v69, v85 row_shr:2 row_mask:0xf bank_mask:0xf
	v_fmac_f32_dpp v210, v70, v86 row_shr:2 row_mask:0xf bank_mask:0xf
	v_fmac_f32_dpp v211, v71, v87 row_shr:2 row_mask:0xf bank_mask:0xf
	v_fmac_f32_dpp v212, v64, v104 row_shr:2 row_mask:0xf bank_mask:0xf
	v_fmac_f32_dpp v213, v65, v105 row_shr:2 row_mask:0xf bank_mask:0xf
	v_fmac_f32_dpp v214, v66, v106 row_shr:2 row_mask:0xf bank_mask:0xf
	v_fmac_f32_dpp v215, v67, v107 row_shr:2 row_mask:0xf bank_mask:0xf
; DI float silu_fast(float x) { return x * __builtin_amdgcn_rcpf(1.f + __expf(-x)); }
; template <int CTRL> DI float dppf(float v) { return __builtin_bit_cast(float, __builtin_amdgcn_update_dpp(0, __builtin_bit_cast(int, v), CTRL, 0xf, 0xf, true)); }
; DI void Epi::fused(const f32x4 (&acc)[2][2][4][2], int pm, int pn, int wr, int wc, int fr, int fq) const {
;     ...
;             for (int m = 0; m < 4; ++m) {
;                 const f32x4 ca = acc[ai][bj][m][0], cb = acc[ai][bj][m][1];
;                 const int row = pm * 256 + ai * 128 + wr * 64 + m * 16 + fr;
;                 float o[4];
; #pragma unroll
;                 for (int e = 0; e < 4; ++e) {
;                     const float a1 = dppf<0x111>(ca[e]) + dppf<0x10F>(pa[e]), a2 = dppf<0x112>(ca[e]) + dppf<0x10E>(pa[e]);
;                     const float b1 = dppf<0x111>(cb[e]) + dppf<0x10F>(pb[e]), b2 = dppf<0x112>(cb[e]) + dppf<0x10E>(pb[e]);
;                     const float ya = fmaf(wa0[e], a2, fmaf(wa1[e], a1, fmaf(wa2[e], ca[e], ba[e])));
;                     const float yb = fmaf(wb0[e], b2, fmaf(wb1[e], b1, fmaf(wb2[e], cb[e], bb[e])));
;                     o[e] = silu_fast(ya) * yb; }
;                 if (m > 0 || fr >= 2) { u32x2 w; w.x = pk2(o[0], o[1]); w.y = pk2(o[2], o[3]); *(u32x2*)(E.d0 + (size_t)row * FFH + j0) = w; }
;                 if ((m == 0 && fr < 2) || (m == 3 && fr >= 14)) { float* hb = E.f0 + ((size_t)(row >> 6) * 4 + (m == 0 ? fr : fr - 12)) * FF2 + ncol; *(f32x4*)hb = ca; *(f32x4*)(hb + 4) = cb; }
	v_fmac_f32_dpp v208, v80, v84 row_shl:14 row_mask:0xf bank_mask:0xf
	v_fmac_f32_dpp v209, v81, v85 row_shl:14 row_mask:0xf bank_mask:0xf
	v_fmac_f32_dpp v210, v82, v86 row_shl:14 row_mask:0xf bank_mask:0xf
	v_fmac_f32_dpp v211, v83, v87 row_shl:14 row_mask:0xf bank_mask:0xf
	v_fmac_f32_dpp v212, v76, v104 row_shl:14 row_mask:0xf bank_mask:0xf
	v_fmac_f32_dpp v213, v77, v105 row_shl:14 row_mask:0xf bank_mask:0xf
	v_fmac_f32_dpp v214, v78, v106 row_shl:14 row_mask:0xf bank_mask:0xf
	v_fmac_f32_dpp v215, v79, v107 row_shl:14 row_mask:0xf bank_mask:0xf
	v_mul_f32_e32 v216, 0xbfb8aa3b, v208
	v_mul_f32_e32 v217, 0xbfb8aa3b, v209
	v_mul_f32_e32 v218, 0xbfb8aa3b, v210
	v_mul_f32_e32 v219, 0xbfb8aa3b, v211
	v_exp_f32_e32 v216, v216
	v_exp_f32_e32 v217, v217
	v_exp_f32_e32 v218, v218
	v_exp_f32_e32 v219, v219
	v_add_f32_e32 v216, 1.0, v216
	v_add_f32_e32 v217, 1.0, v217
	v_add_f32_e32 v218, 1.0, v218
	v_add_f32_e32 v219, 1.0, v219
	v_rcp_f32_e32 v216, v216
	v_rcp_f32_e32 v217, v217
	v_rcp_f32_e32 v218, v218
	v_rcp_f32_e32 v219, v219
	s_mov_b32 s80, 0x42000
	s_mov_b32 s81, 0
	v_lshl_add_u64 v[222:223], v[224:225], 0, s[80:81]
	v_pk_mul_f32 v[208:209], v[208:209], v[216:217]
	v_pk_mul_f32 v[210:211], v[210:211], v[218:219]
	v_pk_mul_f32 v[208:209], v[212:213], v[208:209]
	v_pk_mul_f32 v[210:211], v[214:215], v[210:211]
	v_cvt_pk_bf16_f32 v220, v208, v209
	v_cvt_pk_bf16_f32 v221, v210, v211
	global_store_dwordx2 v[222:223], v[220:221], off
	s_ashr_i32 s80, s71, 6
	s_lshl_b32 s80, s80, 2
	v_add_u32_e32 v226, s80, v190
	v_mov_b64_e32 v[222:223], s[8:9]
	s_movk_i32 s80, 0x5800
	v_mad_i64_i32 v[222:223], s[78:79], v226, s80, v[222:223]
	v_lshl_add_u64 v[222:223], v[228:229], 2, v[222:223]
	s_and_saveexec_b64 s[76:77], s[42:43]
	global_store_dwordx4 v[222:223], v[68:71], off
	global_store_dwordx4 v[222:223], v[64:67], off offset:16
	s_or_b64 exec, exec, s[76:77]
	v_add_u32_e32 v228, 128, v199
	v_mov_b64_e32 v[224:225], s[12:13]
	s_movk_i32 s80, 0x1600
	v_mad_i64_i32 v[224:225], s[78:79], v228, s80, v[224:225]
	v_add_u32_e32 v228, 128, v240
	v_mov_b32_e32 v229, 0
	v_lshl_add_u64 v[224:225], v[228:229], 0, v[224:225]
	v_pk_fma_f32 v[160:161], v[100:101], v[48:49], v[124:125]
	v_pk_fma_f32 v[162:163], v[102:103], v[50:51], v[126:127]
	v_pk_fma_f32 v[164:165], v[120:121], v[44:45], v[72:73]
	v_pk_fma_f32 v[166:167], v[122:123], v[46:47], v[74:75]
	v_fmac_f32_dpp v160, v48, v88 row_shr:1 row_mask:0xf bank_mask:0xf
	v_fmac_f32_dpp v161, v49, v89 row_shr:1 row_mask:0xf bank_mask:0xf
	v_fmac_f32_dpp v162, v50, v90 row_shr:1 row_mask:0xf bank_mask:0xf
	v_fmac_f32_dpp v163, v51, v91 row_shr:1 row_mask:0xf bank_mask:0xf
	v_fmac_f32_dpp v164, v44, v116 row_shr:1 row_mask:0xf bank_mask:0xf
	v_fmac_f32_dpp v165, v45, v117 row_shr:1 row_mask:0xf bank_mask:0xf
	v_fmac_f32_dpp v166, v46, v118 row_shr:1 row_mask:0xf bank_mask:0xf
	v_fmac_f32_dpp v167, v47, v119 row_shr:1 row_mask:0xf bank_mask:0xf
	v_fmac_f32_dpp v160, v48, v84 row_shr:2 row_mask:0xf bank_mask:0xf
	v_fmac_f32_dpp v161, v49, v85 row_shr:2 row_mask:0xf bank_mask:0xf
	v_fmac_f32_dpp v162, v50, v86 row_shr:2 row_mask:0xf bank_mask:0xf
	v_fmac_f32_dpp v163, v51, v87 row_shr:2 row_mask:0xf bank_mask:0xf
	v_fmac_f32_dpp v164, v44, v104 row_shr:2 row_mask:0xf bank_mask:0xf
	v_fmac_f32_dpp v165, v45, v105 row_shr:2 row_mask:0xf bank_mask:0xf
	v_fmac_f32_dpp v166, v46, v106 row_shr:2 row_mask:0xf bank_mask:0xf
	v_fmac_f32_dpp v167, v47, v107 row_shr:2 row_mask:0xf bank_mask:0xf
	v_mul_f32_e32 v168, 0xbfb8aa3b, v160
	v_mul_f32_e32 v169, 0xbfb8aa3b, v161
	v_mul_f32_e32 v170, 0xbfb8aa3b, v162
	v_mul_f32_e32 v171, 0xbfb8aa3b, v163
	v_exp_f32_e32 v168, v168
	v_exp_f32_e32 v169, v169
	v_exp_f32_e32 v170, v170
	v_exp_f32_e32 v171, v171
	v_add_f32_e32 v168, 1.0, v168
	v_add_f32_e32 v169, 1.0, v169
	v_add_f32_e32 v170, 1.0, v170
	v_add_f32_e32 v171, 1.0, v171
	v_rcp_f32_e32 v168, v168
	v_rcp_f32_e32 v169, v169
	v_rcp_f32_e32 v170, v170
	v_rcp_f32_e32 v171, v171
	v_mov_b64_e32 v[174:175], v[224:225]
	v_pk_mul_f32 v[160:161], v[160:161], v[168:169]
	v_pk_mul_f32 v[162:163], v[162:163], v[170:171]
	v_pk_mul_f32 v[160:161], v[164:165], v[160:161]
	v_pk_mul_f32 v[162:163], v[166:167], v[162:163]
	v_cvt_pk_bf16_f32 v172, v160, v161
	v_cvt_pk_bf16_f32 v173, v162, v163
	s_and_saveexec_b64 s[76:77], s[38:39]
	global_store_dwordx2 v[174:175], v[172:173], off
	s_or_b64 exec, exec, s[76:77]
	s_ashr_i32 s80, s71, 6
	s_lshl_b32 s80, s80, 2
	s_add_i32 s80, s80, 8
	v_add_u32_e32 v226, s80, v188
	v_mov_b64_e32 v[174:175], s[8:9]
	s_movk_i32 s80, 0x5800
	v_mad_i64_i32 v[174:175], s[78:79], v226, s80, v[174:175]
	v_lshl_add_u64 v[174:175], v[228:229], 2, v[174:175]
	s_and_saveexec_b64 s[76:77], s[40:41]
	global_store_dwordx4 v[174:175], v[48:51], off
	global_store_dwordx4 v[174:175], v[44:47], off offset:16
	s_or_b64 exec, exec, s[76:77]
	v_pk_fma_f32 v[208:209], v[100:101], v[24:25], v[124:125]
	v_pk_fma_f32 v[210:211], v[102:103], v[26:27], v[126:127]
	v_pk_fma_f32 v[212:213], v[120:121], v[20:21], v[72:73]
	v_pk_fma_f32 v[214:215], v[122:123], v[22:23], v[74:75]
	v_fmac_f32_dpp v208, v24, v88 row_shr:1 row_mask:0xf bank_mask:0xf
	v_fmac_f32_dpp v209, v25, v89 row_shr:1 row_mask:0xf bank_mask:0xf
	v_fmac_f32_dpp v210, v26, v90 row_shr:1 row_mask:0xf bank_mask:0xf
	v_fmac_f32_dpp v211, v27, v91 row_shr:1 row_mask:0xf bank_mask:0xf
	v_fmac_f32_dpp v212, v20, v116 row_shr:1 row_mask:0xf bank_mask:0xf
	v_fmac_f32_dpp v213, v21, v117 row_shr:1 row_mask:0xf bank_mask:0xf
	v_fmac_f32_dpp v214, v22, v118 row_shr:1 row_mask:0xf bank_mask:0xf
	v_fmac_f32_dpp v215, v23, v119 row_shr:1 row_mask:0xf bank_mask:0xf
	v_fmac_f32_dpp v208, v48, v88 row_shl:15 row_mask:0xf bank_mask:0xf
; DI float silu_fast(float x) { return x * __builtin_amdgcn_rcpf(1.f + __expf(-x)); }
; template <int CTRL> DI float dppf(float v) { return __builtin_bit_cast(float, __builtin_amdgcn_update_dpp(0, __builtin_bit_cast(int, v), CTRL, 0xf, 0xf, true)); }
; DI void Epi::fused(const f32x4 (&acc)[2][2][4][2], int pm, int pn, int wr, int wc, int fr, int fq) const {
;     ...
;             for (int m = 0; m < 4; ++m) {
;                 const f32x4 ca = acc[ai][bj][m][0], cb = acc[ai][bj][m][1];
;                 const int row = pm * 256 + ai * 128 + wr * 64 + m * 16 + fr;
;                 float o[4];
; #pragma unroll
;                 for (int e = 0; e < 4; ++e) {
;                     const float a1 = dppf<0x111>(ca[e]) + dppf<0x10F>(pa[e]), a2 = dppf<0x112>(ca[e]) + dppf<0x10E>(pa[e]);
;                     const float b1 = dppf<0x111>(cb[e]) + dppf<0x10F>(pb[e]), b2 = dppf<0x112>(cb[e]) + dppf<0x10E>(pb[e]);
;                     const float ya = fmaf(wa0[e], a2, fmaf(wa1[e], a1, fmaf(wa2[e], ca[e], ba[e])));
;                     const float yb = fmaf(wb0[e], b2, fmaf(wb1[e], b1, fmaf(wb2[e], cb[e], bb[e])));
;                     o[e] = silu_fast(ya) * yb; }
	v_fmac_f32_dpp v209, v49, v89 row_shl:15 row_mask:0xf bank_mask:0xf
	v_fmac_f32_dpp v210, v50, v90 row_shl:15 row_mask:0xf bank_mask:0xf
	v_fmac_f32_dpp v211, v51, v91 row_shl:15 row_mask:0xf bank_mask:0xf
	v_fmac_f32_dpp v212, v44, v116 row_shl:15 row_mask:0xf bank_mask:0xf
	v_fmac_f32_dpp v213, v45, v117 row_shl:15 row_mask:0xf bank_mask:0xf
	v_fmac_f32_dpp v214, v46, v118 row_shl:15 row_mask:0xf bank_mask:0xf
	v_fmac_f32_dpp v215, v47, v119 row_shl:15 row_mask:0xf bank_mask:0xf
	v_fmac_f32_dpp v208, v24, v84 row_shr:2 row_mask:0xf bank_mask:0xf
	v_fmac_f32_dpp v209, v25, v85 row_shr:2 row_mask:0xf bank_mask:0xf
	v_fmac_f32_dpp v210, v26, v86 row_shr:2 row_mask:0xf bank_mask:0xf
	v_fmac_f32_dpp v211, v27, v87 row_shr:2 row_mask:0xf bank_mask:0xf
	v_fmac_f32_dpp v212, v20, v104 row_shr:2 row_mask:0xf bank_mask:0xf
	v_fmac_f32_dpp v213, v21, v105 row_shr:2 row_mask:0xf bank_mask:0xf
	v_fmac_f32_dpp v214, v22, v106 row_shr:2 row_mask:0xf bank_mask:0xf
	v_fmac_f32_dpp v215, v23, v107 row_shr:2 row_mask:0xf bank_mask:0xf
	v_fmac_f32_dpp v208, v48, v84 row_shl:14 row_mask:0xf bank_mask:0xf
	v_fmac_f32_dpp v209, v49, v85 row_shl:14 row_mask:0xf bank_mask:0xf
	v_fmac_f32_dpp v210, v50, v86 row_shl:14 row_mask:0xf bank_mask:0xf
	v_fmac_f32_dpp v211, v51, v87 row_shl:14 row_mask:0xf bank_mask:0xf
	v_fmac_f32_dpp v212, v44, v104 row_shl:14 row_mask:0xf bank_mask:0xf
	v_fmac_f32_dpp v213, v45, v105 row_shl:14 row_mask:0xf bank_mask:0xf
	v_fmac_f32_dpp v214, v46, v106 row_shl:14 row_mask:0xf bank_mask:0xf
	v_fmac_f32_dpp v215, v47, v107 row_shl:14 row_mask:0xf bank_mask:0xf
	v_mul_f32_e32 v216, 0xbfb8aa3b, v208
	v_mul_f32_e32 v217, 0xbfb8aa3b, v209
	v_mul_f32_e32 v218, 0xbfb8aa3b, v210
	v_mul_f32_e32 v219, 0xbfb8aa3b, v211
	v_exp_f32_e32 v216, v216
	v_exp_f32_e32 v217, v217
	v_exp_f32_e32 v218, v218
	v_exp_f32_e32 v219, v219
	v_add_f32_e32 v216, 1.0, v216
	v_add_f32_e32 v217, 1.0, v217
	v_add_f32_e32 v218, 1.0, v218
	v_add_f32_e32 v219, 1.0, v219
	v_rcp_f32_e32 v216, v216
	v_rcp_f32_e32 v217, v217
	v_rcp_f32_e32 v218, v218
	v_rcp_f32_e32 v219, v219
	s_mov_b32 s80, 0x16000
	s_mov_b32 s81, 0
	v_lshl_add_u64 v[222:223], v[224:225], 0, s[80:81]
	v_pk_mul_f32 v[208:209], v[208:209], v[216:217]
	v_pk_mul_f32 v[210:211], v[210:211], v[218:219]
	v_pk_mul_f32 v[208:209], v[212:213], v[208:209]
	v_pk_mul_f32 v[210:211], v[214:215], v[210:211]
	v_cvt_pk_bf16_f32 v220, v208, v209
	v_cvt_pk_bf16_f32 v221, v210, v211
	global_store_dwordx2 v[222:223], v[220:221], off
	v_pk_fma_f32 v[160:161], v[100:101], v[28:29], v[124:125]
	v_pk_fma_f32 v[162:163], v[102:103], v[30:31], v[126:127]
	v_pk_fma_f32 v[164:165], v[120:121], v[32:33], v[72:73]
	v_pk_fma_f32 v[166:167], v[122:123], v[34:35], v[74:75]
	v_fmac_f32_dpp v160, v28, v88 row_shr:1 row_mask:0xf bank_mask:0xf
	v_fmac_f32_dpp v161, v29, v89 row_shr:1 row_mask:0xf bank_mask:0xf
	v_fmac_f32_dpp v162, v30, v90 row_shr:1 row_mask:0xf bank_mask:0xf
	v_fmac_f32_dpp v163, v31, v91 row_shr:1 row_mask:0xf bank_mask:0xf
	v_fmac_f32_dpp v164, v32, v116 row_shr:1 row_mask:0xf bank_mask:0xf
	v_fmac_f32_dpp v165, v33, v117 row_shr:1 row_mask:0xf bank_mask:0xf
	v_fmac_f32_dpp v166, v34, v118 row_shr:1 row_mask:0xf bank_mask:0xf
	v_fmac_f32_dpp v167, v35, v119 row_shr:1 row_mask:0xf bank_mask:0xf
	v_fmac_f32_dpp v160, v24, v88 row_shl:15 row_mask:0xf bank_mask:0xf
	v_fmac_f32_dpp v161, v25, v89 row_shl:15 row_mask:0xf bank_mask:0xf
	v_fmac_f32_dpp v162, v26, v90 row_shl:15 row_mask:0xf bank_mask:0xf
	v_fmac_f32_dpp v163, v27, v91 row_shl:15 row_mask:0xf bank_mask:0xf
	v_fmac_f32_dpp v164, v20, v116 row_shl:15 row_mask:0xf bank_mask:0xf
	v_fmac_f32_dpp v165, v21, v117 row_shl:15 row_mask:0xf bank_mask:0xf
	v_fmac_f32_dpp v166, v22, v118 row_shl:15 row_mask:0xf bank_mask:0xf
	v_fmac_f32_dpp v167, v23, v119 row_shl:15 row_mask:0xf bank_mask:0xf
	v_fmac_f32_dpp v160, v28, v84 row_shr:2 row_mask:0xf bank_mask:0xf
	v_fmac_f32_dpp v161, v29, v85 row_shr:2 row_mask:0xf bank_mask:0xf
	v_fmac_f32_dpp v162, v30, v86 row_shr:2 row_mask:0xf bank_mask:0xf
	v_fmac_f32_dpp v163, v31, v87 row_shr:2 row_mask:0xf bank_mask:0xf
	v_fmac_f32_dpp v164, v32, v104 row_shr:2 row_mask:0xf bank_mask:0xf
	v_fmac_f32_dpp v165, v33, v105 row_shr:2 row_mask:0xf bank_mask:0xf
	v_fmac_f32_dpp v166, v34, v106 row_shr:2 row_mask:0xf bank_mask:0xf
	v_fmac_f32_dpp v167, v35, v107 row_shr:2 row_mask:0xf bank_mask:0xf
	v_fmac_f32_dpp v160, v24, v84 row_shl:14 row_mask:0xf bank_mask:0xf
	v_fmac_f32_dpp v161, v25, v85 row_shl:14 row_mask:0xf bank_mask:0xf
	v_fmac_f32_dpp v162, v26, v86 row_shl:14 row_mask:0xf bank_mask:0xf
	v_fmac_f32_dpp v163, v27, v87 row_shl:14 row_mask:0xf bank_mask:0xf
	v_fmac_f32_dpp v164, v20, v104 row_shl:14 row_mask:0xf bank_mask:0xf
	v_fmac_f32_dpp v165, v21, v105 row_shl:14 row_mask:0xf bank_mask:0xf
; DI float silu_fast(float x) { return x * __builtin_amdgcn_rcpf(1.f + __expf(-x)); }
; template <int CTRL> DI float dppf(float v) { return __builtin_bit_cast(float, __builtin_amdgcn_update_dpp(0, __builtin_bit_cast(int, v), CTRL, 0xf, 0xf, true)); }
; DI void Epi::fused(const f32x4 (&acc)[2][2][4][2], int pm, int pn, int wr, int wc, int fr, int fq) const {
;     ...
;             for (int m = 0; m < 4; ++m) {
;                 const f32x4 ca = acc[ai][bj][m][0], cb = acc[ai][bj][m][1];
;                 const int row = pm * 256 + ai * 128 + wr * 64 + m * 16 + fr;
;                 float o[4];
; #pragma unroll
;                 for (int e = 0; e < 4; ++e) {
;                     const float a1 = dppf<0x111>(ca[e]) + dppf<0x10F>(pa[e]), a2 = dppf<0x112>(ca[e]) + dppf<0x10E>(pa[e]);
;                     const float b1 = dppf<0x111>(cb[e]) + dppf<0x10F>(pb[e]), b2 = dppf<0x112>(cb[e]) + dppf<0x10E>(pb[e]);
;                     const float ya = fmaf(wa0[e], a2, fmaf(wa1[e], a1, fmaf(wa2[e], ca[e], ba[e])));
;                     const float yb = fmaf(wb0[e], b2, fmaf(wb1[e], b1, fmaf(wb2[e], cb[e], bb[e])));
;                     o[e] = silu_fast(ya) * yb; }
;                 if (m > 0 || fr >= 2) { u32x2 w; w.x = pk2(o[0], o[1]); w.y = pk2(o[2], o[3]); *(u32x2*)(E.d0 + (size_t)row * FFH + j0) = w; }
;                 if ((m == 0 && fr < 2) || (m == 3 && fr >= 14)) { float* hb = E.f0 + ((size_t)(row >> 6) * 4 + (m == 0 ? fr : fr - 12)) * FF2 + ncol; *(f32x4*)hb = ca; *(f32x4*)(hb + 4) = cb; }
	v_fmac_f32_dpp v166, v22, v106 row_shl:14 row_mask:0xf bank_mask:0xf
	v_fmac_f32_dpp v167, v23, v107 row_shl:14 row_mask:0xf bank_mask:0xf
	v_mul_f32_e32 v168, 0xbfb8aa3b, v160
	v_mul_f32_e32 v169, 0xbfb8aa3b, v161
	v_mul_f32_e32 v170, 0xbfb8aa3b, v162
	v_mul_f32_e32 v171, 0xbfb8aa3b, v163
	v_exp_f32_e32 v168, v168
	v_exp_f32_e32 v169, v169
	v_exp_f32_e32 v170, v170
	v_exp_f32_e32 v171, v171
	v_add_f32_e32 v168, 1.0, v168
	v_add_f32_e32 v169, 1.0, v169
	v_add_f32_e32 v170, 1.0, v170
	v_add_f32_e32 v171, 1.0, v171
	v_rcp_f32_e32 v168, v168
	v_rcp_f32_e32 v169, v169
	v_rcp_f32_e32 v170, v170
	v_rcp_f32_e32 v171, v171
	s_mov_b32 s80, 0x2c000
	s_mov_b32 s81, 0
	v_lshl_add_u64 v[174:175], v[224:225], 0, s[80:81]
	v_pk_mul_f32 v[160:161], v[160:161], v[168:169]
	v_pk_mul_f32 v[162:163], v[162:163], v[170:171]
	v_pk_mul_f32 v[160:161], v[164:165], v[160:161]
	v_pk_mul_f32 v[162:163], v[166:167], v[162:163]
	v_cvt_pk_bf16_f32 v172, v160, v161
	v_cvt_pk_bf16_f32 v173, v162, v163
	global_store_dwordx2 v[174:175], v[172:173], off
	v_pk_fma_f32 v[208:209], v[100:101], v[8:9], v[124:125]
	v_pk_fma_f32 v[210:211], v[102:103], v[10:11], v[126:127]
	v_pk_fma_f32 v[212:213], v[120:121], v[4:5], v[72:73]
	v_pk_fma_f32 v[214:215], v[122:123], v[6:7], v[74:75]
	v_fmac_f32_dpp v208, v8, v88 row_shr:1 row_mask:0xf bank_mask:0xf
	v_fmac_f32_dpp v209, v9, v89 row_shr:1 row_mask:0xf bank_mask:0xf
	v_fmac_f32_dpp v210, v10, v90 row_shr:1 row_mask:0xf bank_mask:0xf
	v_fmac_f32_dpp v211, v11, v91 row_shr:1 row_mask:0xf bank_mask:0xf
	v_fmac_f32_dpp v212, v4, v116 row_shr:1 row_mask:0xf bank_mask:0xf
	v_fmac_f32_dpp v213, v5, v117 row_shr:1 row_mask:0xf bank_mask:0xf
	v_fmac_f32_dpp v214, v6, v118 row_shr:1 row_mask:0xf bank_mask:0xf
	v_fmac_f32_dpp v215, v7, v119 row_shr:1 row_mask:0xf bank_mask:0xf
	v_fmac_f32_dpp v208, v28, v88 row_shl:15 row_mask:0xf bank_mask:0xf
	v_fmac_f32_dpp v209, v29, v89 row_shl:15 row_mask:0xf bank_mask:0xf
	v_fmac_f32_dpp v210, v30, v90 row_shl:15 row_mask:0xf bank_mask:0xf
	v_fmac_f32_dpp v211, v31, v91 row_shl:15 row_mask:0xf bank_mask:0xf
	v_fmac_f32_dpp v212, v32, v116 row_shl:15 row_mask:0xf bank_mask:0xf
	v_fmac_f32_dpp v213, v33, v117 row_shl:15 row_mask:0xf bank_mask:0xf
	v_fmac_f32_dpp v214, v34, v118 row_shl:15 row_mask:0xf bank_mask:0xf
	v_fmac_f32_dpp v215, v35, v119 row_shl:15 row_mask:0xf bank_mask:0xf
	v_fmac_f32_dpp v208, v8, v84 row_shr:2 row_mask:0xf bank_mask:0xf
	v_fmac_f32_dpp v209, v9, v85 row_shr:2 row_mask:0xf bank_mask:0xf
	v_fmac_f32_dpp v210, v10, v86 row_shr:2 row_mask:0xf bank_mask:0xf
	v_fmac_f32_dpp v211, v11, v87 row_shr:2 row_mask:0xf bank_mask:0xf
	v_fmac_f32_dpp v212, v4, v104 row_shr:2 row_mask:0xf bank_mask:0xf
	v_fmac_f32_dpp v213, v5, v105 row_shr:2 row_mask:0xf bank_mask:0xf
	v_fmac_f32_dpp v214, v6, v106 row_shr:2 row_mask:0xf bank_mask:0xf
	v_fmac_f32_dpp v215, v7, v107 row_shr:2 row_mask:0xf bank_mask:0xf
	v_fmac_f32_dpp v208, v28, v84 row_shl:14 row_mask:0xf bank_mask:0xf
	v_fmac_f32_dpp v209, v29, v85 row_shl:14 row_mask:0xf bank_mask:0xf
	v_fmac_f32_dpp v210, v30, v86 row_shl:14 row_mask:0xf bank_mask:0xf
	v_fmac_f32_dpp v211, v31, v87 row_shl:14 row_mask:0xf bank_mask:0xf
	v_fmac_f32_dpp v212, v32, v104 row_shl:14 row_mask:0xf bank_mask:0xf
	v_fmac_f32_dpp v213, v33, v105 row_shl:14 row_mask:0xf bank_mask:0xf
	v_fmac_f32_dpp v214, v34, v106 row_shl:14 row_mask:0xf bank_mask:0xf
	v_fmac_f32_dpp v215, v35, v107 row_shl:14 row_mask:0xf bank_mask:0xf
	v_mul_f32_e32 v216, 0xbfb8aa3b, v208
	v_mul_f32_e32 v217, 0xbfb8aa3b, v209
	v_mul_f32_e32 v218, 0xbfb8aa3b, v210
	v_mul_f32_e32 v219, 0xbfb8aa3b, v211
	v_exp_f32_e32 v216, v216
	v_exp_f32_e32 v217, v217
	v_exp_f32_e32 v218, v218
	v_exp_f32_e32 v219, v219
	v_add_f32_e32 v216, 1.0, v216
	v_add_f32_e32 v217, 1.0, v217
	v_add_f32_e32 v218, 1.0, v218
	v_add_f32_e32 v219, 1.0, v219
	v_rcp_f32_e32 v216, v216
	v_rcp_f32_e32 v217, v217
	v_rcp_f32_e32 v218, v218
	v_rcp_f32_e32 v219, v219
	s_mov_b32 s80, 0x42000
	s_mov_b32 s81, 0
	v_lshl_add_u64 v[222:223], v[224:225], 0, s[80:81]
	v_pk_mul_f32 v[208:209], v[208:209], v[216:217]
	v_pk_mul_f32 v[210:211], v[210:211], v[218:219]
	v_pk_mul_f32 v[208:209], v[212:213], v[208:209]
	v_pk_mul_f32 v[210:211], v[214:215], v[210:211]
	v_cvt_pk_bf16_f32 v220, v208, v209
	v_cvt_pk_bf16_f32 v221, v210, v211
	global_store_dwordx2 v[222:223], v[220:221], off
	s_ashr_i32 s80, s71, 6
	s_lshl_b32 s80, s80, 2
	s_add_i32 s80, s80, 8
	v_add_u32_e32 v226, s80, v190
	v_mov_b64_e32 v[222:223], s[8:9]
	s_movk_i32 s80, 0x5800
	v_mad_i64_i32 v[222:223], s[78:79], v226, s80, v[222:223]
	v_lshl_add_u64 v[222:223], v[228:229], 2, v[222:223]
	s_and_saveexec_b64 s[76:77], s[42:43]
	global_store_dwordx4 v[222:223], v[8:11], off
	global_store_dwordx4 v[222:223], v[4:7], off offset:16
	s_or_b64 exec, exec, s[76:77]
